# GEMM loop: as best so far but all s_setprio removed from the K-loop
# speedup vs baseline: 1.0188x; 1.0172x over previous
.LBB0_176:
	s_mov_b32 m0, s55
	s_nop 0
	global_load_lds_dwordx4 v194, s[100:101]
	s_mov_b32 m0, s67
	s_nop 0
	global_load_lds_dwordx4 v196, s[100:101]
	v_add_u32_e32 v130, 0x10000, v243
	v_add_u32_e32 v142, 0x14000, v243
	ds_read_b128 v[146:149], v130
	ds_read_b128 v[150:153], v130 offset:1024
	ds_read_b128 v[154:157], v130 offset:2048
	ds_read_b128 v[158:161], v130 offset:3072
	ds_read_b128 v[130:133], v142
	ds_read_b128 v[134:137], v142 offset:1024
	ds_read_b128 v[138:141], v142 offset:2048
	ds_read_b128 v[142:145], v142 offset:3072
	v_lshl_add_u64 v[246:247], v[234:235], 0, s[80:81]
	s_add_i32 m0, s8, 0xc000
	s_waitcnt lgkmcnt(0)
	ds_read_b128 v[174:177], v244
	ds_read_b128 v[190:193], v244 offset:1024
	ds_read_b128 v[170:173], v244 offset:2048
	ds_read_b128 v[186:189], v244 offset:3072
	ds_read_b128 v[166:169], v244 offset:4096
	ds_read_b128 v[182:185], v244 offset:5120
	ds_read_b128 v[162:165], v244 offset:6144
	ds_read_b128 v[178:181], v244 offset:7168
	global_load_lds_dwordx4 v[246:247], off
	v_lshl_add_u64 v[246:247], v[236:237], 0, s[80:81]
	s_add_i32 m0, s8, 0xe000
	s_nop 0
	global_load_lds_dwordx4 v[246:247], off
	s_waitcnt vmcnt(8)
	s_waitcnt lgkmcnt(0)
	s_barrier
	s_waitcnt lgkmcnt(0)
	v_mfma_f32_16x16x32_bf16 v[118:121], v[146:149], v[174:177], v[118:121]
	v_mfma_f32_16x16x32_bf16 v[126:129], v[154:157], v[174:177], v[126:129]
	v_mfma_f32_16x16x32_bf16 v[102:105], v[146:149], v[170:173], v[102:105]
	v_mfma_f32_16x16x32_bf16 v[110:113], v[154:157], v[170:173], v[110:113]
	v_mfma_f32_16x16x32_bf16 v[86:89], v[146:149], v[166:169], v[86:89]
	v_mfma_f32_16x16x32_bf16 v[94:97], v[154:157], v[166:169], v[94:97]
	v_mfma_f32_16x16x32_bf16 v[70:73], v[146:149], v[162:165], v[70:73]
	v_mfma_f32_16x16x32_bf16 v[78:81], v[154:157], v[162:165], v[78:81]
	v_mfma_f32_16x16x32_bf16 v[118:121], v[150:153], v[190:193], v[118:121]
	v_mfma_f32_16x16x32_bf16 v[126:129], v[158:161], v[190:193], v[126:129]
	v_mfma_f32_16x16x32_bf16 v[102:105], v[150:153], v[186:189], v[102:105]
	v_mfma_f32_16x16x32_bf16 v[110:113], v[158:161], v[186:189], v[110:113]
	v_mfma_f32_16x16x32_bf16 v[86:89], v[150:153], v[182:185], v[86:89]
	v_mfma_f32_16x16x32_bf16 v[94:97], v[158:161], v[182:185], v[94:97]
	v_mfma_f32_16x16x32_bf16 v[70:73], v[150:153], v[178:181], v[70:73]
	v_mfma_f32_16x16x32_bf16 v[78:81], v[158:161], v[178:181], v[78:81]
	v_mfma_f32_16x16x32_bf16 v[122:125], v[130:133], v[174:177], v[122:125]
	v_mfma_f32_16x16x32_bf16 v[114:117], v[138:141], v[174:177], v[114:117]
	v_mfma_f32_16x16x32_bf16 v[106:109], v[130:133], v[170:173], v[106:109]
	v_mfma_f32_16x16x32_bf16 v[98:101], v[138:141], v[170:173], v[98:101]
	v_mfma_f32_16x16x32_bf16 v[90:93], v[130:133], v[166:169], v[90:93]
	v_mfma_f32_16x16x32_bf16 v[82:85], v[138:141], v[166:169], v[82:85]
	v_mfma_f32_16x16x32_bf16 v[74:77], v[130:133], v[162:165], v[74:77]
	v_mfma_f32_16x16x32_bf16 v[66:69], v[138:141], v[162:165], v[66:69]
	v_mfma_f32_16x16x32_bf16 v[122:125], v[134:137], v[190:193], v[122:125]
	v_mfma_f32_16x16x32_bf16 v[114:117], v[142:145], v[190:193], v[114:117]
	v_mfma_f32_16x16x32_bf16 v[106:109], v[134:137], v[186:189], v[106:109]
	v_mfma_f32_16x16x32_bf16 v[98:101], v[142:145], v[186:189], v[98:101]
	v_mfma_f32_16x16x32_bf16 v[90:93], v[134:137], v[182:185], v[90:93]
	v_mfma_f32_16x16x32_bf16 v[82:85], v[142:145], v[182:185], v[82:85]
	v_mfma_f32_16x16x32_bf16 v[74:77], v[134:137], v[178:181], v[74:77]
	v_mfma_f32_16x16x32_bf16 v[66:69], v[142:145], v[178:181], v[66:69]
	s_barrier
	v_cndmask_b32_e64 v246, 0, 1, s[50:51]
	v_cmp_ne_u32_e64 s[48:49], 1, v246
	s_andn2_b64 vcc, exec, s[50:51]
	s_cbranch_vccnz .LBB0_178
	ds_read_b128 v[174:177], v244 offset:16384
	ds_read_b128 v[190:193], v244 offset:17408
	ds_read_b128 v[170:173], v244 offset:18432
	ds_read_b128 v[186:189], v244 offset:19456
	ds_read_b128 v[166:169], v244 offset:20480
	ds_read_b128 v[182:185], v244 offset:21504
	ds_read_b128 v[162:165], v244 offset:22528
	ds_read_b128 v[178:181], v244 offset:23552
.LBB0_178:
	s_add_u32 s82, s0, s80
	s_addc_u32 s83, s1, s81
	s_add_u32 s84, s82, 0x460000
	s_addc_u32 s85, s83, 0
	s_cmp_eq_u32 s80, 0x41a0000
	s_cselect_b64 s[86:87], -1, 0
	s_and_b64 s[82:83], s[86:87], exec
	s_cselect_b32 s83, s71, s97
	s_cselect_b32 s82, s73, s79
	s_mov_b32 m0, s9
	s_cselect_b32 s85, s22, s85
	s_cselect_b32 s84, s69, s84
	s_add_u32 vcc_lo, s82, 0x4000
	global_load_lds_dwordx4 v194, s[82:83]
	s_mov_b32 m0, s10
	s_addc_u32 vcc_hi, s83, 0
	global_load_lds_dwordx4 v196, s[82:83]
	s_mov_b32 m0, s11
	s_nop 0
	global_load_lds_dwordx4 v194, vcc
	v_lshl_add_u64 v[246:247], vcc, 0, v[196:197]
	s_mov_b32 m0, s12
	s_and_b64 vcc, exec, s[48:49]
	global_load_lds_dwordx4 v[246:247], off
	s_mov_b64 s[98:99], s[84:85]
	s_waitcnt vmcnt(6)
	s_waitcnt lgkmcnt(0)
	s_barrier
	s_cbranch_vccnz .LBB0_180
	s_waitcnt lgkmcnt(0)
	v_mfma_f32_16x16x32_bf16 v[54:57], v[146:149], v[174:177], v[54:57]
	v_mfma_f32_16x16x32_bf16 v[62:65], v[154:157], v[174:177], v[62:65]
	v_mfma_f32_16x16x32_bf16 v[38:41], v[146:149], v[170:173], v[38:41]
	v_mfma_f32_16x16x32_bf16 v[46:49], v[154:157], v[170:173], v[46:49]
	v_mfma_f32_16x16x32_bf16 v[22:25], v[146:149], v[166:169], v[22:25]
	v_mfma_f32_16x16x32_bf16 v[30:33], v[154:157], v[166:169], v[30:33]
	v_mfma_f32_16x16x32_bf16 v[10:13], v[146:149], v[162:165], v[10:13]
	v_mfma_f32_16x16x32_bf16 v[14:17], v[154:157], v[162:165], v[14:17]
	v_mfma_f32_16x16x32_bf16 v[54:57], v[150:153], v[190:193], v[54:57]
	v_mfma_f32_16x16x32_bf16 v[62:65], v[158:161], v[190:193], v[62:65]
	v_mfma_f32_16x16x32_bf16 v[38:41], v[150:153], v[186:189], v[38:41]
	v_mfma_f32_16x16x32_bf16 v[46:49], v[158:161], v[186:189], v[46:49]
	v_mfma_f32_16x16x32_bf16 v[22:25], v[150:153], v[182:185], v[22:25]
	v_mfma_f32_16x16x32_bf16 v[30:33], v[158:161], v[182:185], v[30:33]
	v_mfma_f32_16x16x32_bf16 v[10:13], v[150:153], v[178:181], v[10:13]
	v_mfma_f32_16x16x32_bf16 v[14:17], v[158:161], v[178:181], v[14:17]
	v_mfma_f32_16x16x32_bf16 v[58:61], v[130:133], v[174:177], v[58:61]
	v_mfma_f32_16x16x32_bf16 v[50:53], v[138:141], v[174:177], v[50:53]
	v_mfma_f32_16x16x32_bf16 v[42:45], v[130:133], v[170:173], v[42:45]
	v_mfma_f32_16x16x32_bf16 v[34:37], v[138:141], v[170:173], v[34:37]
	v_mfma_f32_16x16x32_bf16 v[26:29], v[130:133], v[166:169], v[26:29]
	v_mfma_f32_16x16x32_bf16 v[18:21], v[138:141], v[166:169], v[18:21]
	v_mfma_f32_16x16x32_bf16 v[6:9], v[130:133], v[162:165], v[6:9]
	v_mfma_f32_16x16x32_bf16 v[2:5], v[138:141], v[162:165], v[2:5]
	v_mfma_f32_16x16x32_bf16 v[58:61], v[134:137], v[190:193], v[58:61]
	v_mfma_f32_16x16x32_bf16 v[50:53], v[142:145], v[190:193], v[50:53]
	v_mfma_f32_16x16x32_bf16 v[42:45], v[134:137], v[186:189], v[42:45]
	v_mfma_f32_16x16x32_bf16 v[34:37], v[142:145], v[186:189], v[34:37]
	v_mfma_f32_16x16x32_bf16 v[26:29], v[134:137], v[182:185], v[26:29]
	v_mfma_f32_16x16x32_bf16 v[18:21], v[142:145], v[182:185], v[18:21]
	v_mfma_f32_16x16x32_bf16 v[6:9], v[134:137], v[178:181], v[6:9]
	v_mfma_f32_16x16x32_bf16 v[2:5], v[142:145], v[178:181], v[2:5]
.LBB0_180:
	s_and_b64 vcc, s[46:47], s[86:87]
	v_cndmask_b32_e64 v131, v233, 0, vcc
	v_cndmask_b32_e32 v130, v232, v198, vcc
	v_lshl_add_u64 v[246:247], s[84:85], 0, v[130:131]
	s_barrier
	s_mov_b32 m0, s8
	s_nop 0
	global_load_lds_dwordx4 v194, s[98:99]
	s_mov_b32 m0, s13
	s_nop 0
	global_load_lds_dwordx4 v196, s[98:99]
	v_add_u32_e32 v130, 0x18000, v243
	v_add_u32_e32 v142, 0x1c000, v243
	ds_read_b128 v[146:149], v130
	ds_read_b128 v[150:153], v130 offset:1024
	ds_read_b128 v[154:157], v130 offset:2048
	ds_read_b128 v[158:161], v130 offset:3072
	ds_read_b128 v[130:133], v142
	ds_read_b128 v[134:137], v142 offset:1024
	ds_read_b128 v[138:141], v142 offset:2048
	ds_read_b128 v[142:145], v142 offset:3072
	s_mov_b32 m0, s14
	v_lshl_add_u64 v[248:249], v[246:247], 0, v[194:195]
	s_waitcnt lgkmcnt(0)
	ds_read_b128 v[174:177], v244 offset:32768
	ds_read_b128 v[190:193], v244 offset:33792
	ds_read_b128 v[170:173], v244 offset:34816
	ds_read_b128 v[186:189], v244 offset:35840
	ds_read_b128 v[166:169], v244 offset:36864
	ds_read_b128 v[182:185], v244 offset:37888
	ds_read_b128 v[162:165], v244 offset:38912
	ds_read_b128 v[178:181], v244 offset:39936
	global_load_lds_dwordx4 v[248:249], off
	v_lshl_add_u64 v[246:247], v[246:247], 0, v[196:197]
	s_mov_b32 m0, s15
	s_nop 0
	global_load_lds_dwordx4 v[246:247], off
	s_waitcnt vmcnt(8)
	s_waitcnt lgkmcnt(0)
	s_barrier
	s_waitcnt lgkmcnt(0)
	v_mfma_f32_16x16x32_bf16 v[118:121], v[146:149], v[174:177], v[118:121]
	v_mfma_f32_16x16x32_bf16 v[126:129], v[154:157], v[174:177], v[126:129]
	v_mfma_f32_16x16x32_bf16 v[102:105], v[146:149], v[170:173], v[102:105]
	v_mfma_f32_16x16x32_bf16 v[110:113], v[154:157], v[170:173], v[110:113]
	v_mfma_f32_16x16x32_bf16 v[86:89], v[146:149], v[166:169], v[86:89]
	v_mfma_f32_16x16x32_bf16 v[94:97], v[154:157], v[166:169], v[94:97]
	v_mfma_f32_16x16x32_bf16 v[70:73], v[146:149], v[162:165], v[70:73]
	v_mfma_f32_16x16x32_bf16 v[78:81], v[154:157], v[162:165], v[78:81]
	v_mfma_f32_16x16x32_bf16 v[118:121], v[150:153], v[190:193], v[118:121]
	v_mfma_f32_16x16x32_bf16 v[126:129], v[158:161], v[190:193], v[126:129]
	v_mfma_f32_16x16x32_bf16 v[102:105], v[150:153], v[186:189], v[102:105]
	v_mfma_f32_16x16x32_bf16 v[110:113], v[158:161], v[186:189], v[110:113]
	v_mfma_f32_16x16x32_bf16 v[86:89], v[150:153], v[182:185], v[86:89]
	v_mfma_f32_16x16x32_bf16 v[94:97], v[158:161], v[182:185], v[94:97]
	v_mfma_f32_16x16x32_bf16 v[70:73], v[150:153], v[178:181], v[70:73]
	v_mfma_f32_16x16x32_bf16 v[78:81], v[158:161], v[178:181], v[78:81]
	v_mfma_f32_16x16x32_bf16 v[122:125], v[130:133], v[174:177], v[122:125]
	v_mfma_f32_16x16x32_bf16 v[114:117], v[138:141], v[174:177], v[114:117]
	v_mfma_f32_16x16x32_bf16 v[106:109], v[130:133], v[170:173], v[106:109]
	v_mfma_f32_16x16x32_bf16 v[98:101], v[138:141], v[170:173], v[98:101]
	v_mfma_f32_16x16x32_bf16 v[90:93], v[130:133], v[166:169], v[90:93]
	v_mfma_f32_16x16x32_bf16 v[82:85], v[138:141], v[166:169], v[82:85]
	v_mfma_f32_16x16x32_bf16 v[74:77], v[130:133], v[162:165], v[74:77]
	v_mfma_f32_16x16x32_bf16 v[66:69], v[138:141], v[162:165], v[66:69]
	v_mfma_f32_16x16x32_bf16 v[122:125], v[134:137], v[190:193], v[122:125]
	v_mfma_f32_16x16x32_bf16 v[114:117], v[142:145], v[190:193], v[114:117]
	v_mfma_f32_16x16x32_bf16 v[106:109], v[134:137], v[186:189], v[106:109]
	v_mfma_f32_16x16x32_bf16 v[98:101], v[142:145], v[186:189], v[98:101]
	v_mfma_f32_16x16x32_bf16 v[90:93], v[134:137], v[182:185], v[90:93]
	v_mfma_f32_16x16x32_bf16 v[82:85], v[142:145], v[182:185], v[82:85]
	v_mfma_f32_16x16x32_bf16 v[74:77], v[134:137], v[178:181], v[74:77]
	v_mfma_f32_16x16x32_bf16 v[66:69], v[142:145], v[178:181], v[66:69]
	s_barrier
	s_and_b64 vcc, exec, s[48:49]
	s_cbranch_vccnz .LBB0_182
	ds_read_b128 v[174:177], v244 offset:49152
	ds_read_b128 v[190:193], v244 offset:50176
	ds_read_b128 v[170:173], v244 offset:51200
	ds_read_b128 v[186:189], v244 offset:52224
	ds_read_b128 v[166:169], v244 offset:53248
	ds_read_b128 v[182:185], v244 offset:54272
	ds_read_b128 v[162:165], v244 offset:55296
	ds_read_b128 v[178:181], v244 offset:56320
.LBB0_182:
	s_add_u32 s86, s82, 0x120000
	s_addc_u32 s87, s83, 0
	s_add_u32 s84, s84, 0x230000
	s_addc_u32 s85, s85, 0
	s_mov_b32 m0, s17
	s_add_u32 s82, s82, 0x124000
	global_load_lds_dwordx4 v194, s[86:87]
	s_mov_b32 m0, s54
	s_addc_u32 s83, s83, 0
	global_load_lds_dwordx4 v196, s[86:87]
	s_mov_b32 m0, s89
	s_and_b64 vcc, exec, s[48:49]
	global_load_lds_dwordx4 v194, s[82:83]
	s_mov_b32 m0, s90
	s_nop 0
	global_load_lds_dwordx4 v196, s[82:83]
	s_mov_b64 s[100:101], s[84:85]
	s_waitcnt vmcnt(6)
	s_waitcnt lgkmcnt(0)
	s_barrier
	s_cbranch_vccnz .LBB0_175
	s_waitcnt lgkmcnt(0)
	v_mfma_f32_16x16x32_bf16 v[54:57], v[146:149], v[174:177], v[54:57]
	v_mfma_f32_16x16x32_bf16 v[62:65], v[154:157], v[174:177], v[62:65]
	v_mfma_f32_16x16x32_bf16 v[38:41], v[146:149], v[170:173], v[38:41]
	v_mfma_f32_16x16x32_bf16 v[46:49], v[154:157], v[170:173], v[46:49]
	v_mfma_f32_16x16x32_bf16 v[22:25], v[146:149], v[166:169], v[22:25]
	v_mfma_f32_16x16x32_bf16 v[30:33], v[154:157], v[166:169], v[30:33]
	v_mfma_f32_16x16x32_bf16 v[10:13], v[146:149], v[162:165], v[10:13]
	v_mfma_f32_16x16x32_bf16 v[14:17], v[154:157], v[162:165], v[14:17]
	v_mfma_f32_16x16x32_bf16 v[54:57], v[150:153], v[190:193], v[54:57]
	v_mfma_f32_16x16x32_bf16 v[62:65], v[158:161], v[190:193], v[62:65]
	v_mfma_f32_16x16x32_bf16 v[38:41], v[150:153], v[186:189], v[38:41]
	v_mfma_f32_16x16x32_bf16 v[46:49], v[158:161], v[186:189], v[46:49]
	v_mfma_f32_16x16x32_bf16 v[22:25], v[150:153], v[182:185], v[22:25]
	v_mfma_f32_16x16x32_bf16 v[30:33], v[158:161], v[182:185], v[30:33]
	v_mfma_f32_16x16x32_bf16 v[10:13], v[150:153], v[178:181], v[10:13]
	v_mfma_f32_16x16x32_bf16 v[14:17], v[158:161], v[178:181], v[14:17]
	v_mfma_f32_16x16x32_bf16 v[58:61], v[130:133], v[174:177], v[58:61]
	v_mfma_f32_16x16x32_bf16 v[50:53], v[138:141], v[174:177], v[50:53]
	v_mfma_f32_16x16x32_bf16 v[42:45], v[130:133], v[170:173], v[42:45]
	v_mfma_f32_16x16x32_bf16 v[34:37], v[138:141], v[170:173], v[34:37]
	v_mfma_f32_16x16x32_bf16 v[26:29], v[130:133], v[166:169], v[26:29]
	v_mfma_f32_16x16x32_bf16 v[18:21], v[138:141], v[166:169], v[18:21]
	v_mfma_f32_16x16x32_bf16 v[6:9], v[130:133], v[162:165], v[6:9]
	v_mfma_f32_16x16x32_bf16 v[2:5], v[138:141], v[162:165], v[2:5]
	v_mfma_f32_16x16x32_bf16 v[58:61], v[134:137], v[190:193], v[58:61]
	v_mfma_f32_16x16x32_bf16 v[50:53], v[142:145], v[190:193], v[50:53]
	v_mfma_f32_16x16x32_bf16 v[42:45], v[134:137], v[186:189], v[42:45]
	v_mfma_f32_16x16x32_bf16 v[34:37], v[142:145], v[186:189], v[34:37]
	v_mfma_f32_16x16x32_bf16 v[26:29], v[134:137], v[182:185], v[26:29]
	v_mfma_f32_16x16x32_bf16 v[18:21], v[142:145], v[182:185], v[18:21]
	v_mfma_f32_16x16x32_bf16 v[6:9], v[134:137], v[178:181], v[6:9]
	v_mfma_f32_16x16x32_bf16 v[2:5], v[142:145], v[178:181], v[2:5]
	s_branch .LBB0_175

.LBB0_559:
	s_mov_b32 m0, s55
	s_nop 0
	global_load_lds_dwordx4 v194, s[100:101]
	s_mov_b32 m0, s67
	s_nop 0
	global_load_lds_dwordx4 v196, s[100:101]
	ds_read_b128 v[146:149], v227
	ds_read_b128 v[150:153], v227 offset:1024
	ds_read_b128 v[154:157], v227 offset:2048
	ds_read_b128 v[158:161], v227 offset:3072
	ds_read_b128 v[130:133], v228
	ds_read_b128 v[134:137], v228 offset:1024
	ds_read_b128 v[138:141], v228 offset:2048
	ds_read_b128 v[142:145], v228 offset:3072
	v_lshl_add_u64 v[234:235], v[216:217], 0, s[58:59]
	s_add_i32 m0, s8, 0xc000
	s_waitcnt lgkmcnt(0)
	ds_read_b128 v[174:177], v229
	ds_read_b128 v[190:193], v229 offset:1024
	ds_read_b128 v[170:173], v229 offset:2048
	ds_read_b128 v[186:189], v229 offset:3072
	ds_read_b128 v[166:169], v229 offset:4096
	ds_read_b128 v[182:185], v229 offset:5120
	ds_read_b128 v[162:165], v229 offset:6144
	ds_read_b128 v[178:181], v229 offset:7168
	global_load_lds_dwordx4 v[234:235], off
	v_lshl_add_u64 v[234:235], v[218:219], 0, s[58:59]
	s_add_i32 m0, s8, 0xe000
	s_nop 0
	global_load_lds_dwordx4 v[234:235], off
	s_waitcnt vmcnt(8)
	s_waitcnt lgkmcnt(0)
	s_barrier
	s_waitcnt lgkmcnt(0)
	v_mfma_f32_16x16x32_bf16 v[126:129], v[146:149], v[174:177], v[126:129]
	v_mfma_f32_16x16x32_bf16 v[122:125], v[154:157], v[174:177], v[122:125]
	v_mfma_f32_16x16x32_bf16 v[110:113], v[146:149], v[170:173], v[110:113]
	v_mfma_f32_16x16x32_bf16 v[106:109], v[154:157], v[170:173], v[106:109]
	v_mfma_f32_16x16x32_bf16 v[94:97], v[146:149], v[166:169], v[94:97]
	v_mfma_f32_16x16x32_bf16 v[90:93], v[154:157], v[166:169], v[90:93]
	v_mfma_f32_16x16x32_bf16 v[78:81], v[146:149], v[162:165], v[78:81]
	v_mfma_f32_16x16x32_bf16 v[74:77], v[154:157], v[162:165], v[74:77]
	v_mfma_f32_16x16x32_bf16 v[126:129], v[150:153], v[190:193], v[126:129]
	v_mfma_f32_16x16x32_bf16 v[122:125], v[158:161], v[190:193], v[122:125]
	v_mfma_f32_16x16x32_bf16 v[110:113], v[150:153], v[186:189], v[110:113]
	v_mfma_f32_16x16x32_bf16 v[106:109], v[158:161], v[186:189], v[106:109]
	v_mfma_f32_16x16x32_bf16 v[94:97], v[150:153], v[182:185], v[94:97]
	v_mfma_f32_16x16x32_bf16 v[90:93], v[158:161], v[182:185], v[90:93]
	v_mfma_f32_16x16x32_bf16 v[78:81], v[150:153], v[178:181], v[78:81]
	v_mfma_f32_16x16x32_bf16 v[74:77], v[158:161], v[178:181], v[74:77]
	v_mfma_f32_16x16x32_bf16 v[118:121], v[130:133], v[174:177], v[118:121]
	v_mfma_f32_16x16x32_bf16 v[114:117], v[138:141], v[174:177], v[114:117]
	v_mfma_f32_16x16x32_bf16 v[102:105], v[130:133], v[170:173], v[102:105]
	v_mfma_f32_16x16x32_bf16 v[98:101], v[138:141], v[170:173], v[98:101]
	v_mfma_f32_16x16x32_bf16 v[86:89], v[130:133], v[166:169], v[86:89]
	v_mfma_f32_16x16x32_bf16 v[82:85], v[138:141], v[166:169], v[82:85]
	v_mfma_f32_16x16x32_bf16 v[70:73], v[130:133], v[162:165], v[70:73]
	v_mfma_f32_16x16x32_bf16 v[66:69], v[138:141], v[162:165], v[66:69]
	v_mfma_f32_16x16x32_bf16 v[118:121], v[134:137], v[190:193], v[118:121]
	v_mfma_f32_16x16x32_bf16 v[114:117], v[142:145], v[190:193], v[114:117]
	v_mfma_f32_16x16x32_bf16 v[102:105], v[134:137], v[186:189], v[102:105]
	v_mfma_f32_16x16x32_bf16 v[98:101], v[142:145], v[186:189], v[98:101]
	v_mfma_f32_16x16x32_bf16 v[86:89], v[134:137], v[182:185], v[86:89]
	v_mfma_f32_16x16x32_bf16 v[82:85], v[142:145], v[182:185], v[82:85]
	v_mfma_f32_16x16x32_bf16 v[70:73], v[134:137], v[178:181], v[70:73]
	v_mfma_f32_16x16x32_bf16 v[66:69], v[142:145], v[178:181], v[66:69]
	s_barrier
	v_cmp_ne_u32_e64 s[42:43], 1, v233
	s_andn2_b64 vcc, exec, s[44:45]
	s_cbranch_vccnz .LBB0_561
	ds_read_b128 v[174:177], v229 offset:16384
	ds_read_b128 v[190:193], v229 offset:17408
	ds_read_b128 v[170:173], v229 offset:18432
	ds_read_b128 v[186:189], v229 offset:19456
	ds_read_b128 v[166:169], v229 offset:20480
	ds_read_b128 v[182:185], v229 offset:21504
	ds_read_b128 v[162:165], v229 offset:22528
	ds_read_b128 v[178:181], v229 offset:23552
.LBB0_561:
	s_add_u32 s60, s56, s58
	s_addc_u32 s61, s57, s59
	s_add_u32 s62, s60, 0x440000
	s_addc_u32 s63, s61, 0
	s_cmp_eq_u32 s58, 0x3fc0000
	s_cselect_b64 s[68:69], -1, 0
	s_and_b64 s[60:61], s[68:69], exec
	s_cselect_b32 s61, s37, s72
	s_cselect_b32 s60, s47, s53
	s_mov_b32 m0, s9
	s_cselect_b32 s63, s1, s63
	s_cselect_b32 s62, s24, s62
	s_add_u32 s74, s60, 0x4000
	global_load_lds_dwordx4 v194, s[60:61]
	s_mov_b32 m0, s10
	s_addc_u32 s75, s61, 0
	global_load_lds_dwordx4 v196, s[60:61]
	s_mov_b32 m0, s11
	s_and_b64 vcc, exec, s[42:43]
	global_load_lds_dwordx4 v194, s[74:75]
	s_mov_b32 m0, s12
	s_nop 0
	global_load_lds_dwordx4 v196, s[74:75]
	s_mov_b64 s[98:99], s[62:63]
	s_waitcnt vmcnt(6)
	s_waitcnt lgkmcnt(0)
	s_barrier
	s_cbranch_vccnz .LBB0_563
	s_waitcnt lgkmcnt(0)
	v_mfma_f32_16x16x32_bf16 v[62:65], v[146:149], v[174:177], v[62:65]
	v_mfma_f32_16x16x32_bf16 v[58:61], v[154:157], v[174:177], v[58:61]
	v_mfma_f32_16x16x32_bf16 v[46:49], v[146:149], v[170:173], v[46:49]
	v_mfma_f32_16x16x32_bf16 v[42:45], v[154:157], v[170:173], v[42:45]
	v_mfma_f32_16x16x32_bf16 v[30:33], v[146:149], v[166:169], v[30:33]
	v_mfma_f32_16x16x32_bf16 v[26:29], v[154:157], v[166:169], v[26:29]
	v_mfma_f32_16x16x32_bf16 v[14:17], v[146:149], v[162:165], v[14:17]
	v_mfma_f32_16x16x32_bf16 v[10:13], v[154:157], v[162:165], v[10:13]
	v_mfma_f32_16x16x32_bf16 v[62:65], v[150:153], v[190:193], v[62:65]
	v_mfma_f32_16x16x32_bf16 v[58:61], v[158:161], v[190:193], v[58:61]
	v_mfma_f32_16x16x32_bf16 v[46:49], v[150:153], v[186:189], v[46:49]
	v_mfma_f32_16x16x32_bf16 v[42:45], v[158:161], v[186:189], v[42:45]
	v_mfma_f32_16x16x32_bf16 v[30:33], v[150:153], v[182:185], v[30:33]
	v_mfma_f32_16x16x32_bf16 v[26:29], v[158:161], v[182:185], v[26:29]
	v_mfma_f32_16x16x32_bf16 v[14:17], v[150:153], v[178:181], v[14:17]
	v_mfma_f32_16x16x32_bf16 v[10:13], v[158:161], v[178:181], v[10:13]
	v_mfma_f32_16x16x32_bf16 v[54:57], v[130:133], v[174:177], v[54:57]
	v_mfma_f32_16x16x32_bf16 v[50:53], v[138:141], v[174:177], v[50:53]
	v_mfma_f32_16x16x32_bf16 v[38:41], v[130:133], v[170:173], v[38:41]
	v_mfma_f32_16x16x32_bf16 v[34:37], v[138:141], v[170:173], v[34:37]
	v_mfma_f32_16x16x32_bf16 v[22:25], v[130:133], v[166:169], v[22:25]
	v_mfma_f32_16x16x32_bf16 v[18:21], v[138:141], v[166:169], v[18:21]
	v_mfma_f32_16x16x32_bf16 v[6:9], v[130:133], v[162:165], v[6:9]
	v_mfma_f32_16x16x32_bf16 v[2:5], v[138:141], v[162:165], v[2:5]
	v_mfma_f32_16x16x32_bf16 v[54:57], v[134:137], v[190:193], v[54:57]
	v_mfma_f32_16x16x32_bf16 v[50:53], v[142:145], v[190:193], v[50:53]
	v_mfma_f32_16x16x32_bf16 v[38:41], v[134:137], v[186:189], v[38:41]
	v_mfma_f32_16x16x32_bf16 v[34:37], v[142:145], v[186:189], v[34:37]
	v_mfma_f32_16x16x32_bf16 v[22:25], v[134:137], v[182:185], v[22:25]
	v_mfma_f32_16x16x32_bf16 v[18:21], v[142:145], v[182:185], v[18:21]
	v_mfma_f32_16x16x32_bf16 v[6:9], v[134:137], v[178:181], v[6:9]
	v_mfma_f32_16x16x32_bf16 v[2:5], v[142:145], v[178:181], v[2:5]
.LBB0_563:
	s_and_b64 vcc, s[40:41], s[68:69]
	v_cndmask_b32_e64 v131, v215, 0, vcc
	v_cndmask_b32_e32 v130, v214, v198, vcc
	v_lshl_add_u64 v[234:235], s[62:63], 0, v[130:131]
	s_barrier
	s_mov_b32 m0, s8
	s_nop 0
	global_load_lds_dwordx4 v194, s[98:99]
	s_mov_b32 m0, s13
	s_nop 0
	global_load_lds_dwordx4 v196, s[98:99]
	v_add_u32_e32 v130, 0x18000, v226
	v_add_u32_e32 v142, 0x1c000, v226
	ds_read_b128 v[146:149], v130
	ds_read_b128 v[150:153], v130 offset:1024
	ds_read_b128 v[154:157], v130 offset:2048
	ds_read_b128 v[158:161], v130 offset:3072
	ds_read_b128 v[130:133], v142
	ds_read_b128 v[134:137], v142 offset:1024
	ds_read_b128 v[138:141], v142 offset:2048
	ds_read_b128 v[142:145], v142 offset:3072
	s_mov_b32 m0, s14
	v_lshl_add_u64 v[236:237], v[234:235], 0, v[194:195]
	s_waitcnt lgkmcnt(0)
	ds_read_b128 v[174:177], v229 offset:32768
	ds_read_b128 v[190:193], v229 offset:33792
	ds_read_b128 v[170:173], v229 offset:34816
	ds_read_b128 v[186:189], v229 offset:35840
	ds_read_b128 v[166:169], v229 offset:36864
	ds_read_b128 v[182:185], v229 offset:37888
	ds_read_b128 v[162:165], v229 offset:38912
	ds_read_b128 v[178:181], v229 offset:39936
	global_load_lds_dwordx4 v[236:237], off
	v_lshl_add_u64 v[234:235], v[234:235], 0, v[196:197]
	s_mov_b32 m0, s15
	s_nop 0
	global_load_lds_dwordx4 v[234:235], off
	s_waitcnt vmcnt(8)
	s_waitcnt lgkmcnt(0)
	s_barrier
	s_waitcnt lgkmcnt(0)
	v_mfma_f32_16x16x32_bf16 v[126:129], v[146:149], v[174:177], v[126:129]
	v_mfma_f32_16x16x32_bf16 v[122:125], v[154:157], v[174:177], v[122:125]
	v_mfma_f32_16x16x32_bf16 v[110:113], v[146:149], v[170:173], v[110:113]
	v_mfma_f32_16x16x32_bf16 v[106:109], v[154:157], v[170:173], v[106:109]
	v_mfma_f32_16x16x32_bf16 v[94:97], v[146:149], v[166:169], v[94:97]
	v_mfma_f32_16x16x32_bf16 v[90:93], v[154:157], v[166:169], v[90:93]
	v_mfma_f32_16x16x32_bf16 v[78:81], v[146:149], v[162:165], v[78:81]
	v_mfma_f32_16x16x32_bf16 v[74:77], v[154:157], v[162:165], v[74:77]
	v_mfma_f32_16x16x32_bf16 v[126:129], v[150:153], v[190:193], v[126:129]
	v_mfma_f32_16x16x32_bf16 v[122:125], v[158:161], v[190:193], v[122:125]
	v_mfma_f32_16x16x32_bf16 v[110:113], v[150:153], v[186:189], v[110:113]
	v_mfma_f32_16x16x32_bf16 v[106:109], v[158:161], v[186:189], v[106:109]
	v_mfma_f32_16x16x32_bf16 v[94:97], v[150:153], v[182:185], v[94:97]
	v_mfma_f32_16x16x32_bf16 v[90:93], v[158:161], v[182:185], v[90:93]
	v_mfma_f32_16x16x32_bf16 v[78:81], v[150:153], v[178:181], v[78:81]
	v_mfma_f32_16x16x32_bf16 v[74:77], v[158:161], v[178:181], v[74:77]
	v_mfma_f32_16x16x32_bf16 v[118:121], v[130:133], v[174:177], v[118:121]
	v_mfma_f32_16x16x32_bf16 v[114:117], v[138:141], v[174:177], v[114:117]
	v_mfma_f32_16x16x32_bf16 v[102:105], v[130:133], v[170:173], v[102:105]
	v_mfma_f32_16x16x32_bf16 v[98:101], v[138:141], v[170:173], v[98:101]
	v_mfma_f32_16x16x32_bf16 v[86:89], v[130:133], v[166:169], v[86:89]
	v_mfma_f32_16x16x32_bf16 v[82:85], v[138:141], v[166:169], v[82:85]
	v_mfma_f32_16x16x32_bf16 v[70:73], v[130:133], v[162:165], v[70:73]
	v_mfma_f32_16x16x32_bf16 v[66:69], v[138:141], v[162:165], v[66:69]
	v_mfma_f32_16x16x32_bf16 v[118:121], v[134:137], v[190:193], v[118:121]
	v_mfma_f32_16x16x32_bf16 v[114:117], v[142:145], v[190:193], v[114:117]
	v_mfma_f32_16x16x32_bf16 v[102:105], v[134:137], v[186:189], v[102:105]
	v_mfma_f32_16x16x32_bf16 v[98:101], v[142:145], v[186:189], v[98:101]
	v_mfma_f32_16x16x32_bf16 v[86:89], v[134:137], v[182:185], v[86:89]
	v_mfma_f32_16x16x32_bf16 v[82:85], v[142:145], v[182:185], v[82:85]
	v_mfma_f32_16x16x32_bf16 v[70:73], v[134:137], v[178:181], v[70:73]
	v_mfma_f32_16x16x32_bf16 v[66:69], v[142:145], v[178:181], v[66:69]
	s_barrier
	s_and_b64 vcc, exec, s[42:43]
	s_cbranch_vccnz .LBB0_565
	ds_read_b128 v[174:177], v229 offset:49152
	ds_read_b128 v[190:193], v229 offset:50176
	ds_read_b128 v[170:173], v229 offset:51200
	ds_read_b128 v[186:189], v229 offset:52224
	ds_read_b128 v[166:169], v229 offset:53248
	ds_read_b128 v[182:185], v229 offset:54272
	ds_read_b128 v[162:165], v229 offset:55296
	ds_read_b128 v[178:181], v229 offset:56320
.LBB0_565:
	s_add_u32 s68, s60, 0x40000
	s_addc_u32 s69, s61, 0
	s_add_u32 s62, s62, 0x220000
	s_addc_u32 s63, s63, 0
	s_mov_b32 m0, s17
	s_add_u32 s60, s60, 0x44000
	global_load_lds_dwordx4 v194, s[68:69]
	s_mov_b32 m0, s54
	s_addc_u32 s61, s61, 0
	global_load_lds_dwordx4 v196, s[68:69]
	s_mov_b32 m0, s70
	s_and_b64 vcc, exec, s[42:43]
	global_load_lds_dwordx4 v194, s[60:61]
	s_mov_b32 m0, s71
	s_nop 0
	global_load_lds_dwordx4 v196, s[60:61]
	s_mov_b64 s[100:101], s[62:63]
	s_waitcnt vmcnt(6)
	s_waitcnt lgkmcnt(0)
	s_barrier
	s_cbranch_vccnz .LBB0_558
	s_waitcnt lgkmcnt(0)
	v_mfma_f32_16x16x32_bf16 v[62:65], v[146:149], v[174:177], v[62:65]
	v_mfma_f32_16x16x32_bf16 v[58:61], v[154:157], v[174:177], v[58:61]
	v_mfma_f32_16x16x32_bf16 v[46:49], v[146:149], v[170:173], v[46:49]
	v_mfma_f32_16x16x32_bf16 v[42:45], v[154:157], v[170:173], v[42:45]
	v_mfma_f32_16x16x32_bf16 v[30:33], v[146:149], v[166:169], v[30:33]
	v_mfma_f32_16x16x32_bf16 v[26:29], v[154:157], v[166:169], v[26:29]
	v_mfma_f32_16x16x32_bf16 v[14:17], v[146:149], v[162:165], v[14:17]
	v_mfma_f32_16x16x32_bf16 v[10:13], v[154:157], v[162:165], v[10:13]
	v_mfma_f32_16x16x32_bf16 v[62:65], v[150:153], v[190:193], v[62:65]
	v_mfma_f32_16x16x32_bf16 v[58:61], v[158:161], v[190:193], v[58:61]
	v_mfma_f32_16x16x32_bf16 v[46:49], v[150:153], v[186:189], v[46:49]
	v_mfma_f32_16x16x32_bf16 v[42:45], v[158:161], v[186:189], v[42:45]
	v_mfma_f32_16x16x32_bf16 v[30:33], v[150:153], v[182:185], v[30:33]
	v_mfma_f32_16x16x32_bf16 v[26:29], v[158:161], v[182:185], v[26:29]
	v_mfma_f32_16x16x32_bf16 v[14:17], v[150:153], v[178:181], v[14:17]
	v_mfma_f32_16x16x32_bf16 v[10:13], v[158:161], v[178:181], v[10:13]
	v_mfma_f32_16x16x32_bf16 v[54:57], v[130:133], v[174:177], v[54:57]
	v_mfma_f32_16x16x32_bf16 v[50:53], v[138:141], v[174:177], v[50:53]
	v_mfma_f32_16x16x32_bf16 v[38:41], v[130:133], v[170:173], v[38:41]
	v_mfma_f32_16x16x32_bf16 v[34:37], v[138:141], v[170:173], v[34:37]
	v_mfma_f32_16x16x32_bf16 v[22:25], v[130:133], v[166:169], v[22:25]
	v_mfma_f32_16x16x32_bf16 v[18:21], v[138:141], v[166:169], v[18:21]
	v_mfma_f32_16x16x32_bf16 v[6:9], v[130:133], v[162:165], v[6:9]
	v_mfma_f32_16x16x32_bf16 v[2:5], v[138:141], v[162:165], v[2:5]
	v_mfma_f32_16x16x32_bf16 v[54:57], v[134:137], v[190:193], v[54:57]
	v_mfma_f32_16x16x32_bf16 v[50:53], v[142:145], v[190:193], v[50:53]
	v_mfma_f32_16x16x32_bf16 v[38:41], v[134:137], v[186:189], v[38:41]
	v_mfma_f32_16x16x32_bf16 v[34:37], v[142:145], v[186:189], v[34:37]
	v_mfma_f32_16x16x32_bf16 v[22:25], v[134:137], v[182:185], v[22:25]
	v_mfma_f32_16x16x32_bf16 v[18:21], v[142:145], v[182:185], v[18:21]
	v_mfma_f32_16x16x32_bf16 v[6:9], v[134:137], v[178:181], v[6:9]
	v_mfma_f32_16x16x32_bf16 v[2:5], v[142:145], v[178:181], v[2:5]
	s_branch .LBB0_558

.LBB0_761:
	s_mov_b32 m0, s14
	s_nop 0
	global_load_lds_dwordx4 v194, s[100:101]
	s_mov_b32 m0, s15
	s_nop 0
	global_load_lds_dwordx4 v196, s[100:101]
	ds_read_b128 v[130:133], v237
	ds_read_b128 v[134:137], v237 offset:1024
	ds_read_b128 v[138:141], v237 offset:2048
	ds_read_b128 v[142:145], v237 offset:3072
	ds_read_b128 v[146:149], v238
	ds_read_b128 v[150:153], v238 offset:1024
	ds_read_b128 v[154:157], v238 offset:2048
	ds_read_b128 v[158:161], v238 offset:3072
	s_add_u32 s48, s0, 0x21c000
	s_addc_u32 s49, s1, 0
	s_cmp_eq_u32 s67, 28
	s_cselect_b32 s42, s55, s62
	s_cselect_b32 s43, s29, s63
	s_cselect_b32 s52, s45, s48
	s_cselect_b32 s53, s31, s49
	s_add_u32 s50, s42, 0xe0000
	s_addc_u32 s51, s43, 0
	s_add_u32 s48, s52, 0x220000
	s_addc_u32 s49, s53, 0
	v_lshl_add_u64 v[208:209], s[0:1], 0, v[202:203]
	s_add_i32 m0, s9, 0xc000
	ds_read_b128 v[162:165], v239
	ds_read_b128 v[166:169], v239 offset:1024
	ds_read_b128 v[170:173], v239 offset:2048
	ds_read_b128 v[174:177], v239 offset:3072
	ds_read_b128 v[178:181], v239 offset:4096
	ds_read_b128 v[182:185], v239 offset:5120
	ds_read_b128 v[186:189], v239 offset:6144
	ds_read_b128 v[190:193], v239 offset:7168
	global_load_lds_dwordx4 v[208:209], off
	v_lshl_add_u64 v[208:209], s[0:1], 0, v[200:201]
	s_add_i32 m0, s9, 0xe000
	s_nop 0
	global_load_lds_dwordx4 v[208:209], off
	s_waitcnt vmcnt(8)
	s_waitcnt lgkmcnt(0)
	s_barrier
	s_waitcnt lgkmcnt(0)
	v_mfma_f32_16x16x32_bf16 v[126:129], v[130:133], v[162:165], v[126:129]
	v_mfma_f32_16x16x32_bf16 v[122:125], v[138:141], v[162:165], v[122:125]
	v_mfma_f32_16x16x32_bf16 v[118:121], v[130:133], v[170:173], v[118:121]
	v_mfma_f32_16x16x32_bf16 v[114:117], v[138:141], v[170:173], v[114:117]
	v_mfma_f32_16x16x32_bf16 v[110:113], v[130:133], v[178:181], v[110:113]
	v_mfma_f32_16x16x32_bf16 v[106:109], v[138:141], v[178:181], v[106:109]
	v_mfma_f32_16x16x32_bf16 v[102:105], v[130:133], v[186:189], v[102:105]
	v_mfma_f32_16x16x32_bf16 v[98:101], v[138:141], v[186:189], v[98:101]
	v_mfma_f32_16x16x32_bf16 v[126:129], v[134:137], v[166:169], v[126:129]
	v_mfma_f32_16x16x32_bf16 v[122:125], v[142:145], v[166:169], v[122:125]
	v_mfma_f32_16x16x32_bf16 v[118:121], v[134:137], v[174:177], v[118:121]
	v_mfma_f32_16x16x32_bf16 v[114:117], v[142:145], v[174:177], v[114:117]
	v_mfma_f32_16x16x32_bf16 v[110:113], v[134:137], v[182:185], v[110:113]
	v_mfma_f32_16x16x32_bf16 v[106:109], v[142:145], v[182:185], v[106:109]
	v_mfma_f32_16x16x32_bf16 v[102:105], v[134:137], v[190:193], v[102:105]
	v_mfma_f32_16x16x32_bf16 v[98:101], v[142:145], v[190:193], v[98:101]
	v_mfma_f32_16x16x32_bf16 v[62:65], v[146:149], v[162:165], v[62:65]
	s_add_u32 s60, s52, 0x4000
	s_addc_u32 s61, s53, 0
	v_mfma_f32_16x16x32_bf16 v[58:61], v[154:157], v[162:165], v[58:61]
	v_mfma_f32_16x16x32_bf16 v[54:57], v[146:149], v[170:173], v[54:57]
	v_mfma_f32_16x16x32_bf16 v[50:53], v[154:157], v[170:173], v[50:53]
	v_mfma_f32_16x16x32_bf16 v[46:49], v[146:149], v[178:181], v[46:49]
	v_mfma_f32_16x16x32_bf16 v[42:45], v[154:157], v[178:181], v[42:45]
	v_mfma_f32_16x16x32_bf16 v[38:41], v[146:149], v[186:189], v[38:41]
	v_mfma_f32_16x16x32_bf16 v[34:37], v[154:157], v[186:189], v[34:37]
	v_mfma_f32_16x16x32_bf16 v[62:65], v[150:153], v[166:169], v[62:65]
	v_mfma_f32_16x16x32_bf16 v[58:61], v[158:161], v[166:169], v[58:61]
	v_mfma_f32_16x16x32_bf16 v[54:57], v[150:153], v[174:177], v[54:57]
	v_mfma_f32_16x16x32_bf16 v[50:53], v[158:161], v[174:177], v[50:53]
	v_mfma_f32_16x16x32_bf16 v[46:49], v[150:153], v[182:185], v[46:49]
	v_mfma_f32_16x16x32_bf16 v[42:45], v[158:161], v[182:185], v[42:45]
	v_mfma_f32_16x16x32_bf16 v[38:41], v[150:153], v[190:193], v[38:41]
	v_mfma_f32_16x16x32_bf16 v[34:37], v[158:161], v[190:193], v[34:37]
	s_barrier
	s_add_i32 s68, s16, s8
	s_mov_b32 m0, s68
	ds_read_b128 v[162:165], v239 offset:16384
	ds_read_b128 v[166:169], v239 offset:17408
	ds_read_b128 v[170:173], v239 offset:18432
	ds_read_b128 v[174:177], v239 offset:19456
	ds_read_b128 v[178:181], v239 offset:20480
	ds_read_b128 v[182:185], v239 offset:21504
	ds_read_b128 v[186:189], v239 offset:22528
	ds_read_b128 v[190:193], v239 offset:23552
	global_load_lds_dwordx4 v194, s[42:43]
	s_add_i32 m0, s68, 0x2000
	s_add_u32 s68, s42, 0x4000
	s_addc_u32 s69, s43, 0
	s_add_i32 s70, s17, s8
	global_load_lds_dwordx4 v196, s[42:43]
	s_mov_b32 m0, s70
	s_nop 0
	global_load_lds_dwordx4 v194, s[68:69]
	s_add_i32 m0, s70, 0x2000
	s_nop 0
	global_load_lds_dwordx4 v196, s[68:69]
	s_mov_b64 s[98:99], s[52:53]
	s_waitcnt vmcnt(6)
	s_waitcnt lgkmcnt(0)
	s_barrier
	s_waitcnt lgkmcnt(0)
	v_mfma_f32_16x16x32_bf16 v[94:97], v[130:133], v[162:165], v[94:97]
	v_mfma_f32_16x16x32_bf16 v[90:93], v[138:141], v[162:165], v[90:93]
	v_mfma_f32_16x16x32_bf16 v[86:89], v[130:133], v[170:173], v[86:89]
	v_mfma_f32_16x16x32_bf16 v[82:85], v[138:141], v[170:173], v[82:85]
	v_mfma_f32_16x16x32_bf16 v[78:81], v[130:133], v[178:181], v[78:81]
	v_mfma_f32_16x16x32_bf16 v[74:77], v[138:141], v[178:181], v[74:77]
	v_mfma_f32_16x16x32_bf16 v[70:73], v[130:133], v[186:189], v[70:73]
	v_mfma_f32_16x16x32_bf16 v[66:69], v[138:141], v[186:189], v[66:69]
	v_mfma_f32_16x16x32_bf16 v[94:97], v[134:137], v[166:169], v[94:97]
	v_mfma_f32_16x16x32_bf16 v[90:93], v[142:145], v[166:169], v[90:93]
	v_mfma_f32_16x16x32_bf16 v[86:89], v[134:137], v[174:177], v[86:89]
	v_mfma_f32_16x16x32_bf16 v[82:85], v[142:145], v[174:177], v[82:85]
	v_mfma_f32_16x16x32_bf16 v[78:81], v[134:137], v[182:185], v[78:81]
	v_mfma_f32_16x16x32_bf16 v[74:77], v[142:145], v[182:185], v[74:77]
	v_mfma_f32_16x16x32_bf16 v[70:73], v[134:137], v[190:193], v[70:73]
	v_mfma_f32_16x16x32_bf16 v[66:69], v[142:145], v[190:193], v[66:69]
	v_mfma_f32_16x16x32_bf16 v[30:33], v[146:149], v[162:165], v[30:33]
	v_mfma_f32_16x16x32_bf16 v[26:29], v[154:157], v[162:165], v[26:29]
	v_mfma_f32_16x16x32_bf16 v[22:25], v[146:149], v[170:173], v[22:25]
	v_mfma_f32_16x16x32_bf16 v[18:21], v[154:157], v[170:173], v[18:21]
	v_mfma_f32_16x16x32_bf16 v[14:17], v[146:149], v[178:181], v[14:17]
	v_mfma_f32_16x16x32_bf16 v[10:13], v[154:157], v[178:181], v[10:13]
	v_mfma_f32_16x16x32_bf16 v[6:9], v[146:149], v[186:189], v[6:9]
	v_mfma_f32_16x16x32_bf16 v[2:5], v[154:157], v[186:189], v[2:5]
	v_mfma_f32_16x16x32_bf16 v[30:33], v[150:153], v[166:169], v[30:33]
	v_mfma_f32_16x16x32_bf16 v[26:29], v[158:161], v[166:169], v[26:29]
	v_mfma_f32_16x16x32_bf16 v[22:25], v[150:153], v[174:177], v[22:25]
	v_mfma_f32_16x16x32_bf16 v[18:21], v[158:161], v[174:177], v[18:21]
	v_mfma_f32_16x16x32_bf16 v[14:17], v[150:153], v[182:185], v[14:17]
	v_mfma_f32_16x16x32_bf16 v[10:13], v[158:161], v[182:185], v[10:13]
	v_mfma_f32_16x16x32_bf16 v[6:9], v[150:153], v[190:193], v[6:9]
	v_mfma_f32_16x16x32_bf16 v[2:5], v[158:161], v[190:193], v[2:5]
	s_barrier
	s_mov_b32 m0, s9
	s_nop 0
	global_load_lds_dwordx4 v194, s[98:99]
	s_mov_b32 m0, s10
	s_nop 0
	global_load_lds_dwordx4 v196, s[98:99]
	s_add_i32 s52, 0, 0x18000
	s_add_i32 s53, 0, 0x1c000
	v_add_u32_e32 v142, s52, v228
	v_add_u32_e32 v158, s53, v228
	ds_read_b128 v[130:133], v142
	ds_read_b128 v[134:137], v142 offset:1024
	ds_read_b128 v[138:141], v142 offset:2048
	ds_read_b128 v[142:145], v142 offset:3072
	ds_read_b128 v[146:149], v158
	ds_read_b128 v[150:153], v158 offset:1024
	ds_read_b128 v[154:157], v158 offset:2048
	ds_read_b128 v[158:161], v158 offset:3072
	s_mov_b32 m0, s11
	ds_read_b128 v[162:165], v239 offset:32768
	ds_read_b128 v[166:169], v239 offset:33792
	ds_read_b128 v[170:173], v239 offset:34816
	ds_read_b128 v[174:177], v239 offset:35840
	ds_read_b128 v[178:181], v239 offset:36864
	ds_read_b128 v[182:185], v239 offset:37888
	ds_read_b128 v[186:189], v239 offset:38912
	ds_read_b128 v[190:193], v239 offset:39936
	global_load_lds_dwordx4 v194, s[60:61]
	s_mov_b32 m0, s12
	s_nop 0
	global_load_lds_dwordx4 v196, s[60:61]
	s_waitcnt vmcnt(8)
	s_waitcnt lgkmcnt(0)
	s_barrier
	s_waitcnt lgkmcnt(0)
	v_mfma_f32_16x16x32_bf16 v[126:129], v[130:133], v[162:165], v[126:129]
	v_mfma_f32_16x16x32_bf16 v[122:125], v[138:141], v[162:165], v[122:125]
	v_mfma_f32_16x16x32_bf16 v[118:121], v[130:133], v[170:173], v[118:121]
	v_mfma_f32_16x16x32_bf16 v[114:117], v[138:141], v[170:173], v[114:117]
	v_mfma_f32_16x16x32_bf16 v[110:113], v[130:133], v[178:181], v[110:113]
	v_mfma_f32_16x16x32_bf16 v[106:109], v[138:141], v[178:181], v[106:109]
	v_mfma_f32_16x16x32_bf16 v[102:105], v[130:133], v[186:189], v[102:105]
	v_mfma_f32_16x16x32_bf16 v[98:101], v[138:141], v[186:189], v[98:101]
	v_mfma_f32_16x16x32_bf16 v[126:129], v[134:137], v[166:169], v[126:129]
	v_mfma_f32_16x16x32_bf16 v[122:125], v[142:145], v[166:169], v[122:125]
	v_mfma_f32_16x16x32_bf16 v[118:121], v[134:137], v[174:177], v[118:121]
	v_mfma_f32_16x16x32_bf16 v[114:117], v[142:145], v[174:177], v[114:117]
	v_mfma_f32_16x16x32_bf16 v[110:113], v[134:137], v[182:185], v[110:113]
	v_mfma_f32_16x16x32_bf16 v[106:109], v[142:145], v[182:185], v[106:109]
	v_mfma_f32_16x16x32_bf16 v[102:105], v[134:137], v[190:193], v[102:105]
	v_mfma_f32_16x16x32_bf16 v[98:101], v[142:145], v[190:193], v[98:101]
	v_mfma_f32_16x16x32_bf16 v[62:65], v[146:149], v[162:165], v[62:65]
	v_mfma_f32_16x16x32_bf16 v[58:61], v[154:157], v[162:165], v[58:61]
	v_mfma_f32_16x16x32_bf16 v[54:57], v[146:149], v[170:173], v[54:57]
	v_mfma_f32_16x16x32_bf16 v[50:53], v[154:157], v[170:173], v[50:53]
	v_mfma_f32_16x16x32_bf16 v[46:49], v[146:149], v[178:181], v[46:49]
	v_mfma_f32_16x16x32_bf16 v[42:45], v[154:157], v[178:181], v[42:45]
	v_mfma_f32_16x16x32_bf16 v[38:41], v[146:149], v[186:189], v[38:41]
	v_mfma_f32_16x16x32_bf16 v[34:37], v[154:157], v[186:189], v[34:37]
	v_mfma_f32_16x16x32_bf16 v[62:65], v[150:153], v[166:169], v[62:65]
	v_mfma_f32_16x16x32_bf16 v[58:61], v[158:161], v[166:169], v[58:61]
	v_mfma_f32_16x16x32_bf16 v[54:57], v[150:153], v[174:177], v[54:57]
	v_mfma_f32_16x16x32_bf16 v[50:53], v[158:161], v[174:177], v[50:53]
	v_mfma_f32_16x16x32_bf16 v[46:49], v[150:153], v[182:185], v[46:49]
	v_mfma_f32_16x16x32_bf16 v[42:45], v[158:161], v[182:185], v[42:45]
	v_mfma_f32_16x16x32_bf16 v[38:41], v[150:153], v[190:193], v[38:41]
	v_mfma_f32_16x16x32_bf16 v[34:37], v[158:161], v[190:193], v[34:37]
	s_barrier
	s_add_i32 s52, s52, s8
	s_mov_b32 m0, s52
	ds_read_b128 v[162:165], v239 offset:49152
	ds_read_b128 v[166:169], v239 offset:50176
	ds_read_b128 v[170:173], v239 offset:51200
	ds_read_b128 v[174:177], v239 offset:52224
	ds_read_b128 v[178:181], v239 offset:53248
	ds_read_b128 v[182:185], v239 offset:54272
	ds_read_b128 v[186:189], v239 offset:55296
	ds_read_b128 v[190:193], v239 offset:56320
	global_load_lds_dwordx4 v194, s[50:51]
	s_add_i32 m0, s52, 0x2000
	s_add_u32 s42, s42, 0xe4000
	v_lshl_add_u64 v[208:209], s[50:51], 0, v[196:197]
	s_addc_u32 s43, s43, 0
	s_add_i32 s50, s53, s8
	global_load_lds_dwordx4 v[208:209], off
	s_mov_b32 m0, s50
	s_nop 0
	global_load_lds_dwordx4 v194, s[42:43]
	s_add_i32 m0, s50, 0x2000
	s_nop 0
	global_load_lds_dwordx4 v196, s[42:43]
	s_mov_b64 s[100:101], s[48:49]
	s_waitcnt vmcnt(6)
	s_waitcnt lgkmcnt(0)
	s_barrier
	s_waitcnt lgkmcnt(0)
	v_mfma_f32_16x16x32_bf16 v[94:97], v[130:133], v[162:165], v[94:97]
	v_mfma_f32_16x16x32_bf16 v[90:93], v[138:141], v[162:165], v[90:93]
	v_mfma_f32_16x16x32_bf16 v[86:89], v[130:133], v[170:173], v[86:89]
	v_mfma_f32_16x16x32_bf16 v[82:85], v[138:141], v[170:173], v[82:85]
	v_mfma_f32_16x16x32_bf16 v[78:81], v[130:133], v[178:181], v[78:81]
	v_mfma_f32_16x16x32_bf16 v[74:77], v[138:141], v[178:181], v[74:77]
	v_mfma_f32_16x16x32_bf16 v[70:73], v[130:133], v[186:189], v[70:73]
	v_mfma_f32_16x16x32_bf16 v[66:69], v[138:141], v[186:189], v[66:69]
	v_mfma_f32_16x16x32_bf16 v[94:97], v[134:137], v[166:169], v[94:97]
	v_mfma_f32_16x16x32_bf16 v[90:93], v[142:145], v[166:169], v[90:93]
	v_mfma_f32_16x16x32_bf16 v[86:89], v[134:137], v[174:177], v[86:89]
	v_mfma_f32_16x16x32_bf16 v[82:85], v[142:145], v[174:177], v[82:85]
	v_mfma_f32_16x16x32_bf16 v[78:81], v[134:137], v[182:185], v[78:81]
	v_mfma_f32_16x16x32_bf16 v[74:77], v[142:145], v[182:185], v[74:77]
	v_mfma_f32_16x16x32_bf16 v[70:73], v[134:137], v[190:193], v[70:73]
	v_mfma_f32_16x16x32_bf16 v[66:69], v[142:145], v[190:193], v[66:69]
	v_mfma_f32_16x16x32_bf16 v[30:33], v[146:149], v[162:165], v[30:33]
	v_mfma_f32_16x16x32_bf16 v[26:29], v[154:157], v[162:165], v[26:29]
	v_mfma_f32_16x16x32_bf16 v[22:25], v[146:149], v[170:173], v[22:25]
	v_mfma_f32_16x16x32_bf16 v[18:21], v[154:157], v[170:173], v[18:21]
	v_mfma_f32_16x16x32_bf16 v[14:17], v[146:149], v[178:181], v[14:17]
	v_mfma_f32_16x16x32_bf16 v[10:13], v[154:157], v[178:181], v[10:13]
	v_mfma_f32_16x16x32_bf16 v[6:9], v[146:149], v[186:189], v[6:9]
	v_mfma_f32_16x16x32_bf16 v[2:5], v[154:157], v[186:189], v[2:5]
	v_mfma_f32_16x16x32_bf16 v[30:33], v[150:153], v[166:169], v[30:33]
	v_mfma_f32_16x16x32_bf16 v[26:29], v[158:161], v[166:169], v[26:29]
	v_mfma_f32_16x16x32_bf16 v[22:25], v[150:153], v[174:177], v[22:25]
	v_mfma_f32_16x16x32_bf16 v[18:21], v[158:161], v[174:177], v[18:21]
	v_mfma_f32_16x16x32_bf16 v[14:17], v[150:153], v[182:185], v[14:17]
	v_mfma_f32_16x16x32_bf16 v[10:13], v[158:161], v[182:185], v[10:13]
	v_mfma_f32_16x16x32_bf16 v[6:9], v[150:153], v[190:193], v[6:9]
	v_mfma_f32_16x16x32_bf16 v[2:5], v[158:161], v[190:193], v[2:5]
	s_barrier
	s_add_i32 s67, s67, 2
	s_add_u32 s62, s62, 0x1c0000
	s_addc_u32 s63, s63, 0
	s_add_u32 s0, s0, 0x440000
	s_addc_u32 s1, s1, 0
	s_cmp_gt_u32 s67, 29
	s_cbranch_scc0 .LBB0_761
	s_and_b64 vcc, exec, s[26:27]
	s_cbranch_vccz .LBB0_764
	s_barrier

.LBB0_903:
	s_mov_b32 m0, s23
	s_nop 0
	global_load_lds_dwordx4 v194, s[100:101]
	s_mov_b32 m0, s31
	s_nop 0
	global_load_lds_dwordx4 v196, s[100:101]
	ds_read_b128 v[146:149], v225
	ds_read_b128 v[150:153], v225 offset:1024
	ds_read_b128 v[154:157], v225 offset:2048
	ds_read_b128 v[158:161], v225 offset:3072
	ds_read_b128 v[130:133], v227
	ds_read_b128 v[134:137], v227 offset:1024
	ds_read_b128 v[138:141], v227 offset:2048
	ds_read_b128 v[142:145], v227 offset:3072
	v_lshl_add_u64 v[234:235], v[210:211], 0, s[62:63]
	s_add_i32 m0, s8, 0xc000
	s_waitcnt lgkmcnt(0)
	ds_read_b128 v[174:177], v228
	ds_read_b128 v[190:193], v228 offset:1024
	ds_read_b128 v[170:173], v228 offset:2048
	ds_read_b128 v[186:189], v228 offset:3072
	ds_read_b128 v[166:169], v228 offset:4096
	ds_read_b128 v[182:185], v228 offset:5120
	ds_read_b128 v[162:165], v228 offset:6144
	ds_read_b128 v[178:181], v228 offset:7168
	global_load_lds_dwordx4 v[234:235], off
	v_lshl_add_u64 v[234:235], v[212:213], 0, s[62:63]
	s_add_i32 m0, s8, 0xe000
	s_nop 0
	global_load_lds_dwordx4 v[234:235], off
	s_waitcnt vmcnt(8)
	s_waitcnt lgkmcnt(0)
	s_barrier
	s_waitcnt lgkmcnt(0)
	v_mfma_f32_16x16x32_bf16 v[126:129], v[146:149], v[174:177], v[126:129]
	v_mfma_f32_16x16x32_bf16 v[122:125], v[154:157], v[174:177], v[122:125]
	v_mfma_f32_16x16x32_bf16 v[118:121], v[146:149], v[170:173], v[118:121]
	v_mfma_f32_16x16x32_bf16 v[114:117], v[154:157], v[170:173], v[114:117]
	v_mfma_f32_16x16x32_bf16 v[110:113], v[146:149], v[166:169], v[110:113]
	v_mfma_f32_16x16x32_bf16 v[106:109], v[154:157], v[166:169], v[106:109]
	v_mfma_f32_16x16x32_bf16 v[102:105], v[146:149], v[162:165], v[102:105]
	v_mfma_f32_16x16x32_bf16 v[98:101], v[154:157], v[162:165], v[98:101]
	v_mfma_f32_16x16x32_bf16 v[126:129], v[150:153], v[190:193], v[126:129]
	v_mfma_f32_16x16x32_bf16 v[122:125], v[158:161], v[190:193], v[122:125]
	v_mfma_f32_16x16x32_bf16 v[118:121], v[150:153], v[186:189], v[118:121]
	v_mfma_f32_16x16x32_bf16 v[114:117], v[158:161], v[186:189], v[114:117]
	v_mfma_f32_16x16x32_bf16 v[110:113], v[150:153], v[182:185], v[110:113]
	v_mfma_f32_16x16x32_bf16 v[106:109], v[158:161], v[182:185], v[106:109]
	v_mfma_f32_16x16x32_bf16 v[102:105], v[150:153], v[178:181], v[102:105]
	v_mfma_f32_16x16x32_bf16 v[98:101], v[158:161], v[178:181], v[98:101]
	v_mfma_f32_16x16x32_bf16 v[94:97], v[130:133], v[174:177], v[94:97]
	v_mfma_f32_16x16x32_bf16 v[90:93], v[138:141], v[174:177], v[90:93]
	v_mfma_f32_16x16x32_bf16 v[86:89], v[130:133], v[170:173], v[86:89]
	v_mfma_f32_16x16x32_bf16 v[82:85], v[138:141], v[170:173], v[82:85]
	v_mfma_f32_16x16x32_bf16 v[78:81], v[130:133], v[166:169], v[78:81]
	v_mfma_f32_16x16x32_bf16 v[74:77], v[138:141], v[166:169], v[74:77]
	v_mfma_f32_16x16x32_bf16 v[70:73], v[130:133], v[162:165], v[70:73]
	v_mfma_f32_16x16x32_bf16 v[66:69], v[138:141], v[162:165], v[66:69]
	v_mfma_f32_16x16x32_bf16 v[94:97], v[134:137], v[190:193], v[94:97]
	v_mfma_f32_16x16x32_bf16 v[90:93], v[142:145], v[190:193], v[90:93]
	v_mfma_f32_16x16x32_bf16 v[86:89], v[134:137], v[186:189], v[86:89]
	v_mfma_f32_16x16x32_bf16 v[82:85], v[142:145], v[186:189], v[82:85]
	v_mfma_f32_16x16x32_bf16 v[78:81], v[134:137], v[182:185], v[78:81]
	v_mfma_f32_16x16x32_bf16 v[74:77], v[142:145], v[182:185], v[74:77]
	v_mfma_f32_16x16x32_bf16 v[70:73], v[134:137], v[178:181], v[70:73]
	v_mfma_f32_16x16x32_bf16 v[66:69], v[142:145], v[178:181], v[66:69]
	s_barrier
	v_cmp_ne_u32_e64 s[42:43], 1, v233
	s_andn2_b64 vcc, exec, s[44:45]
	s_cbranch_vccnz .LBB0_905
	ds_read_b128 v[174:177], v228 offset:16384
	ds_read_b128 v[190:193], v228 offset:17408
	ds_read_b128 v[170:173], v228 offset:18432
	ds_read_b128 v[186:189], v228 offset:19456
	ds_read_b128 v[166:169], v228 offset:20480
	ds_read_b128 v[182:185], v228 offset:21504
	ds_read_b128 v[162:165], v228 offset:22528
	ds_read_b128 v[178:181], v228 offset:23552
.LBB0_905:
	s_add_u32 s68, s0, s62
	s_addc_u32 s69, s1, s63
	s_add_u32 s70, s68, 0x440000
	s_addc_u32 s71, s69, 0
	s_cmp_eq_u32 s62, 0x3fc0000
	s_cselect_b64 s[72:73], -1, 0
	s_and_b64 s[68:69], s[72:73], exec
	s_cselect_b32 s69, s37, s77
	s_cselect_b32 s68, s75, s76
	s_mov_b32 m0, s9
	s_cselect_b32 s71, s35, s71
	s_cselect_b32 s70, s74, s70
	s_add_u32 s80, s68, 0x4000
	global_load_lds_dwordx4 v194, s[68:69]
	s_mov_b32 m0, s10
	s_addc_u32 s81, s69, 0
	global_load_lds_dwordx4 v196, s[68:69]
	s_mov_b32 m0, s11
	s_and_b64 vcc, exec, s[42:43]
	global_load_lds_dwordx4 v194, s[80:81]
	s_mov_b32 m0, s12
	s_nop 0
	global_load_lds_dwordx4 v196, s[80:81]
	s_mov_b64 s[98:99], s[70:71]
	s_waitcnt vmcnt(6)
	s_waitcnt lgkmcnt(0)
	s_barrier
	s_cbranch_vccnz .LBB0_907
	s_waitcnt lgkmcnt(0)
	v_mfma_f32_16x16x32_bf16 v[62:65], v[146:149], v[174:177], v[62:65]
	v_mfma_f32_16x16x32_bf16 v[58:61], v[154:157], v[174:177], v[58:61]
	v_mfma_f32_16x16x32_bf16 v[54:57], v[146:149], v[170:173], v[54:57]
	v_mfma_f32_16x16x32_bf16 v[50:53], v[154:157], v[170:173], v[50:53]
	v_mfma_f32_16x16x32_bf16 v[46:49], v[146:149], v[166:169], v[46:49]
	v_mfma_f32_16x16x32_bf16 v[42:45], v[154:157], v[166:169], v[42:45]
	v_mfma_f32_16x16x32_bf16 v[38:41], v[146:149], v[162:165], v[38:41]
	v_mfma_f32_16x16x32_bf16 v[34:37], v[154:157], v[162:165], v[34:37]
	v_mfma_f32_16x16x32_bf16 v[62:65], v[150:153], v[190:193], v[62:65]
	v_mfma_f32_16x16x32_bf16 v[58:61], v[158:161], v[190:193], v[58:61]
	v_mfma_f32_16x16x32_bf16 v[54:57], v[150:153], v[186:189], v[54:57]
	v_mfma_f32_16x16x32_bf16 v[50:53], v[158:161], v[186:189], v[50:53]
	v_mfma_f32_16x16x32_bf16 v[46:49], v[150:153], v[182:185], v[46:49]
	v_mfma_f32_16x16x32_bf16 v[42:45], v[158:161], v[182:185], v[42:45]
	v_mfma_f32_16x16x32_bf16 v[38:41], v[150:153], v[178:181], v[38:41]
	v_mfma_f32_16x16x32_bf16 v[34:37], v[158:161], v[178:181], v[34:37]
	v_mfma_f32_16x16x32_bf16 v[30:33], v[130:133], v[174:177], v[30:33]
	v_mfma_f32_16x16x32_bf16 v[26:29], v[138:141], v[174:177], v[26:29]
	v_mfma_f32_16x16x32_bf16 v[22:25], v[130:133], v[170:173], v[22:25]
	v_mfma_f32_16x16x32_bf16 v[18:21], v[138:141], v[170:173], v[18:21]
	v_mfma_f32_16x16x32_bf16 v[14:17], v[130:133], v[166:169], v[14:17]
	v_mfma_f32_16x16x32_bf16 v[10:13], v[138:141], v[166:169], v[10:13]
	v_mfma_f32_16x16x32_bf16 v[6:9], v[130:133], v[162:165], v[6:9]
	v_mfma_f32_16x16x32_bf16 v[2:5], v[138:141], v[162:165], v[2:5]
	v_mfma_f32_16x16x32_bf16 v[30:33], v[134:137], v[190:193], v[30:33]
	v_mfma_f32_16x16x32_bf16 v[26:29], v[142:145], v[190:193], v[26:29]
	v_mfma_f32_16x16x32_bf16 v[22:25], v[134:137], v[186:189], v[22:25]
	v_mfma_f32_16x16x32_bf16 v[18:21], v[142:145], v[186:189], v[18:21]
	v_mfma_f32_16x16x32_bf16 v[14:17], v[134:137], v[182:185], v[14:17]
	v_mfma_f32_16x16x32_bf16 v[10:13], v[142:145], v[182:185], v[10:13]
	v_mfma_f32_16x16x32_bf16 v[6:9], v[134:137], v[178:181], v[6:9]
	v_mfma_f32_16x16x32_bf16 v[2:5], v[142:145], v[178:181], v[2:5]
.LBB0_907:
	s_and_b64 vcc, s[40:41], s[72:73]
	v_cndmask_b32_e64 v131, v209, 0, vcc
	v_cndmask_b32_e32 v130, v208, v198, vcc
	v_lshl_add_u64 v[234:235], s[70:71], 0, v[130:131]
	s_barrier
	s_mov_b32 m0, s8
	s_nop 0
	global_load_lds_dwordx4 v194, s[98:99]
	s_mov_b32 m0, s13
	s_nop 0
	global_load_lds_dwordx4 v196, s[98:99]
	v_add_u32_e32 v130, 0x18000, v224
	v_add_u32_e32 v142, 0x1c000, v224
	ds_read_b128 v[146:149], v130
	ds_read_b128 v[150:153], v130 offset:1024
	ds_read_b128 v[154:157], v130 offset:2048
	ds_read_b128 v[158:161], v130 offset:3072
	ds_read_b128 v[130:133], v142
	ds_read_b128 v[134:137], v142 offset:1024
	ds_read_b128 v[138:141], v142 offset:2048
	ds_read_b128 v[142:145], v142 offset:3072
	s_mov_b32 m0, s14
	v_lshl_add_u64 v[236:237], v[234:235], 0, v[194:195]
	s_waitcnt lgkmcnt(0)
	ds_read_b128 v[174:177], v228 offset:32768
	ds_read_b128 v[190:193], v228 offset:33792
	ds_read_b128 v[170:173], v228 offset:34816
	ds_read_b128 v[186:189], v228 offset:35840
	ds_read_b128 v[166:169], v228 offset:36864
	ds_read_b128 v[182:185], v228 offset:37888
	ds_read_b128 v[162:165], v228 offset:38912
	ds_read_b128 v[178:181], v228 offset:39936
	global_load_lds_dwordx4 v[236:237], off
	v_lshl_add_u64 v[234:235], v[234:235], 0, v[196:197]
	s_mov_b32 m0, s15
	s_nop 0
	global_load_lds_dwordx4 v[234:235], off
	s_waitcnt vmcnt(8)
	s_waitcnt lgkmcnt(0)
	s_barrier
	s_waitcnt lgkmcnt(0)
	v_mfma_f32_16x16x32_bf16 v[126:129], v[146:149], v[174:177], v[126:129]
	v_mfma_f32_16x16x32_bf16 v[122:125], v[154:157], v[174:177], v[122:125]
	v_mfma_f32_16x16x32_bf16 v[118:121], v[146:149], v[170:173], v[118:121]
	v_mfma_f32_16x16x32_bf16 v[114:117], v[154:157], v[170:173], v[114:117]
	v_mfma_f32_16x16x32_bf16 v[110:113], v[146:149], v[166:169], v[110:113]
	v_mfma_f32_16x16x32_bf16 v[106:109], v[154:157], v[166:169], v[106:109]
	v_mfma_f32_16x16x32_bf16 v[102:105], v[146:149], v[162:165], v[102:105]
	v_mfma_f32_16x16x32_bf16 v[98:101], v[154:157], v[162:165], v[98:101]
	v_mfma_f32_16x16x32_bf16 v[126:129], v[150:153], v[190:193], v[126:129]
	v_mfma_f32_16x16x32_bf16 v[122:125], v[158:161], v[190:193], v[122:125]
	v_mfma_f32_16x16x32_bf16 v[118:121], v[150:153], v[186:189], v[118:121]
	v_mfma_f32_16x16x32_bf16 v[114:117], v[158:161], v[186:189], v[114:117]
	v_mfma_f32_16x16x32_bf16 v[110:113], v[150:153], v[182:185], v[110:113]
	v_mfma_f32_16x16x32_bf16 v[106:109], v[158:161], v[182:185], v[106:109]
	v_mfma_f32_16x16x32_bf16 v[102:105], v[150:153], v[178:181], v[102:105]
	v_mfma_f32_16x16x32_bf16 v[98:101], v[158:161], v[178:181], v[98:101]
	v_mfma_f32_16x16x32_bf16 v[94:97], v[130:133], v[174:177], v[94:97]
	v_mfma_f32_16x16x32_bf16 v[90:93], v[138:141], v[174:177], v[90:93]
	v_mfma_f32_16x16x32_bf16 v[86:89], v[130:133], v[170:173], v[86:89]
	v_mfma_f32_16x16x32_bf16 v[82:85], v[138:141], v[170:173], v[82:85]
	v_mfma_f32_16x16x32_bf16 v[78:81], v[130:133], v[166:169], v[78:81]
	v_mfma_f32_16x16x32_bf16 v[74:77], v[138:141], v[166:169], v[74:77]
	v_mfma_f32_16x16x32_bf16 v[70:73], v[130:133], v[162:165], v[70:73]
	v_mfma_f32_16x16x32_bf16 v[66:69], v[138:141], v[162:165], v[66:69]
	v_mfma_f32_16x16x32_bf16 v[94:97], v[134:137], v[190:193], v[94:97]
	v_mfma_f32_16x16x32_bf16 v[90:93], v[142:145], v[190:193], v[90:93]
	v_mfma_f32_16x16x32_bf16 v[86:89], v[134:137], v[186:189], v[86:89]
	v_mfma_f32_16x16x32_bf16 v[82:85], v[142:145], v[186:189], v[82:85]
	v_mfma_f32_16x16x32_bf16 v[78:81], v[134:137], v[182:185], v[78:81]
	v_mfma_f32_16x16x32_bf16 v[74:77], v[142:145], v[182:185], v[74:77]
	v_mfma_f32_16x16x32_bf16 v[70:73], v[134:137], v[178:181], v[70:73]
	v_mfma_f32_16x16x32_bf16 v[66:69], v[142:145], v[178:181], v[66:69]
	s_barrier
	s_and_b64 vcc, exec, s[42:43]
	s_cbranch_vccnz .LBB0_909
	ds_read_b128 v[174:177], v228 offset:49152
	ds_read_b128 v[190:193], v228 offset:50176
	ds_read_b128 v[170:173], v228 offset:51200
	ds_read_b128 v[186:189], v228 offset:52224
	ds_read_b128 v[166:169], v228 offset:53248
	ds_read_b128 v[182:185], v228 offset:54272
	ds_read_b128 v[162:165], v228 offset:55296
	ds_read_b128 v[178:181], v228 offset:56320
.LBB0_909:
	s_add_u32 s72, s68, 0xe0000
	s_addc_u32 s73, s69, 0
	s_add_u32 s70, s70, 0x220000
	s_addc_u32 s71, s71, 0
	s_mov_b32 m0, s16
	s_add_u32 s68, s68, 0xe4000
	global_load_lds_dwordx4 v194, s[72:73]
	s_mov_b32 m0, s17
	s_addc_u32 s69, s69, 0
	global_load_lds_dwordx4 v196, s[72:73]
	s_mov_b32 m0, s54
	s_and_b64 vcc, exec, s[42:43]
	global_load_lds_dwordx4 v194, s[68:69]
	s_mov_b32 m0, s55
	s_nop 0
	global_load_lds_dwordx4 v196, s[68:69]
	s_mov_b64 s[100:101], s[70:71]
	s_waitcnt vmcnt(6)
	s_waitcnt lgkmcnt(0)
	s_barrier
	s_cbranch_vccnz .LBB0_902
	s_waitcnt lgkmcnt(0)
	v_mfma_f32_16x16x32_bf16 v[62:65], v[146:149], v[174:177], v[62:65]
	v_mfma_f32_16x16x32_bf16 v[58:61], v[154:157], v[174:177], v[58:61]
	v_mfma_f32_16x16x32_bf16 v[54:57], v[146:149], v[170:173], v[54:57]
	v_mfma_f32_16x16x32_bf16 v[50:53], v[154:157], v[170:173], v[50:53]
	v_mfma_f32_16x16x32_bf16 v[46:49], v[146:149], v[166:169], v[46:49]
	v_mfma_f32_16x16x32_bf16 v[42:45], v[154:157], v[166:169], v[42:45]
	v_mfma_f32_16x16x32_bf16 v[38:41], v[146:149], v[162:165], v[38:41]
	v_mfma_f32_16x16x32_bf16 v[34:37], v[154:157], v[162:165], v[34:37]
	v_mfma_f32_16x16x32_bf16 v[62:65], v[150:153], v[190:193], v[62:65]
	v_mfma_f32_16x16x32_bf16 v[58:61], v[158:161], v[190:193], v[58:61]
	v_mfma_f32_16x16x32_bf16 v[54:57], v[150:153], v[186:189], v[54:57]
	v_mfma_f32_16x16x32_bf16 v[50:53], v[158:161], v[186:189], v[50:53]
	v_mfma_f32_16x16x32_bf16 v[46:49], v[150:153], v[182:185], v[46:49]
	v_mfma_f32_16x16x32_bf16 v[42:45], v[158:161], v[182:185], v[42:45]
	v_mfma_f32_16x16x32_bf16 v[38:41], v[150:153], v[178:181], v[38:41]
	v_mfma_f32_16x16x32_bf16 v[34:37], v[158:161], v[178:181], v[34:37]
	v_mfma_f32_16x16x32_bf16 v[30:33], v[130:133], v[174:177], v[30:33]
	v_mfma_f32_16x16x32_bf16 v[26:29], v[138:141], v[174:177], v[26:29]
	v_mfma_f32_16x16x32_bf16 v[22:25], v[130:133], v[170:173], v[22:25]
	v_mfma_f32_16x16x32_bf16 v[18:21], v[138:141], v[170:173], v[18:21]
	v_mfma_f32_16x16x32_bf16 v[14:17], v[130:133], v[166:169], v[14:17]
	v_mfma_f32_16x16x32_bf16 v[10:13], v[138:141], v[166:169], v[10:13]
	v_mfma_f32_16x16x32_bf16 v[6:9], v[130:133], v[162:165], v[6:9]
	v_mfma_f32_16x16x32_bf16 v[2:5], v[138:141], v[162:165], v[2:5]
	v_mfma_f32_16x16x32_bf16 v[30:33], v[134:137], v[190:193], v[30:33]
	v_mfma_f32_16x16x32_bf16 v[26:29], v[142:145], v[190:193], v[26:29]
	v_mfma_f32_16x16x32_bf16 v[22:25], v[134:137], v[186:189], v[22:25]
	v_mfma_f32_16x16x32_bf16 v[18:21], v[142:145], v[186:189], v[18:21]
	v_mfma_f32_16x16x32_bf16 v[14:17], v[134:137], v[182:185], v[14:17]
	v_mfma_f32_16x16x32_bf16 v[10:13], v[142:145], v[182:185], v[10:13]
	v_mfma_f32_16x16x32_bf16 v[6:9], v[134:137], v[178:181], v[6:9]
	v_mfma_f32_16x16x32_bf16 v[2:5], v[142:145], v[178:181], v[2:5]
	s_branch .LBB0_902

.LBB0_1289:
	s_mov_b32 m0, s27
	s_nop 0
	global_load_lds_dwordx4 v194, s[100:101]
	s_mov_b32 m0, s54
	s_nop 0
	global_load_lds_dwordx4 v196, s[100:101]
	v_add_u32_e32 v142, 0x14000, v229
	ds_read_b128 v[146:149], v230
	ds_read_b128 v[150:153], v230 offset:1024
	ds_read_b128 v[154:157], v230 offset:2048
	ds_read_b128 v[158:161], v230 offset:3072
	ds_read_b128 v[130:133], v142
	ds_read_b128 v[134:137], v142 offset:1024
	ds_read_b128 v[138:141], v142 offset:2048
	ds_read_b128 v[142:145], v142 offset:3072
	v_lshl_add_u64 v[234:235], v[222:223], 0, s[48:49]
	s_add_i32 m0, s8, 0xc000
	s_waitcnt lgkmcnt(0)
	ds_read_b128 v[174:177], v231
	ds_read_b128 v[190:193], v231 offset:1024
	ds_read_b128 v[170:173], v231 offset:2048
	ds_read_b128 v[186:189], v231 offset:3072
	ds_read_b128 v[166:169], v231 offset:4096
	ds_read_b128 v[182:185], v231 offset:5120
	ds_read_b128 v[162:165], v231 offset:6144
	ds_read_b128 v[178:181], v231 offset:7168
	global_load_lds_dwordx4 v[234:235], off
	v_lshl_add_u64 v[234:235], v[224:225], 0, s[48:49]
	s_add_i32 m0, s8, 0xe000
	s_nop 0
	global_load_lds_dwordx4 v[234:235], off
	s_waitcnt vmcnt(8)
	s_waitcnt lgkmcnt(0)
	s_barrier
	s_waitcnt lgkmcnt(0)
	v_mfma_f32_16x16x32_bf16 v[126:129], v[146:149], v[174:177], v[126:129]
	v_mfma_f32_16x16x32_bf16 v[122:125], v[154:157], v[174:177], v[122:125]
	v_mfma_f32_16x16x32_bf16 v[118:121], v[146:149], v[170:173], v[118:121]
	v_mfma_f32_16x16x32_bf16 v[110:113], v[154:157], v[170:173], v[110:113]
	v_mfma_f32_16x16x32_bf16 v[102:105], v[146:149], v[166:169], v[102:105]
	v_mfma_f32_16x16x32_bf16 v[94:97], v[154:157], v[166:169], v[94:97]
	v_mfma_f32_16x16x32_bf16 v[86:89], v[146:149], v[162:165], v[86:89]
	v_mfma_f32_16x16x32_bf16 v[78:81], v[154:157], v[162:165], v[78:81]
	v_mfma_f32_16x16x32_bf16 v[126:129], v[150:153], v[190:193], v[126:129]
	v_mfma_f32_16x16x32_bf16 v[122:125], v[158:161], v[190:193], v[122:125]
	v_mfma_f32_16x16x32_bf16 v[118:121], v[150:153], v[186:189], v[118:121]
	v_mfma_f32_16x16x32_bf16 v[110:113], v[158:161], v[186:189], v[110:113]
	v_mfma_f32_16x16x32_bf16 v[102:105], v[150:153], v[182:185], v[102:105]
	v_mfma_f32_16x16x32_bf16 v[94:97], v[158:161], v[182:185], v[94:97]
	v_mfma_f32_16x16x32_bf16 v[86:89], v[150:153], v[178:181], v[86:89]
	v_mfma_f32_16x16x32_bf16 v[78:81], v[158:161], v[178:181], v[78:81]
	v_mfma_f32_16x16x32_bf16 v[114:117], v[130:133], v[174:177], v[114:117]
	v_mfma_f32_16x16x32_bf16 v[106:109], v[138:141], v[174:177], v[106:109]
	v_mfma_f32_16x16x32_bf16 v[98:101], v[130:133], v[170:173], v[98:101]
	v_mfma_f32_16x16x32_bf16 v[90:93], v[138:141], v[170:173], v[90:93]
	v_mfma_f32_16x16x32_bf16 v[82:85], v[130:133], v[166:169], v[82:85]
	v_mfma_f32_16x16x32_bf16 v[74:77], v[138:141], v[166:169], v[74:77]
	v_mfma_f32_16x16x32_bf16 v[70:73], v[130:133], v[162:165], v[70:73]
	v_mfma_f32_16x16x32_bf16 v[66:69], v[138:141], v[162:165], v[66:69]
	v_mfma_f32_16x16x32_bf16 v[114:117], v[134:137], v[190:193], v[114:117]
	v_mfma_f32_16x16x32_bf16 v[106:109], v[142:145], v[190:193], v[106:109]
	v_mfma_f32_16x16x32_bf16 v[98:101], v[134:137], v[186:189], v[98:101]
	v_mfma_f32_16x16x32_bf16 v[90:93], v[142:145], v[186:189], v[90:93]
	v_mfma_f32_16x16x32_bf16 v[82:85], v[134:137], v[182:185], v[82:85]
	v_mfma_f32_16x16x32_bf16 v[74:77], v[142:145], v[182:185], v[74:77]
	v_mfma_f32_16x16x32_bf16 v[70:73], v[134:137], v[178:181], v[70:73]
	v_mfma_f32_16x16x32_bf16 v[66:69], v[142:145], v[178:181], v[66:69]
	s_barrier
	v_cndmask_b32_e64 v233, 0, 1, s[40:41]
	v_cmp_ne_u32_e64 s[42:43], 1, v233
	s_andn2_b64 vcc, exec, s[40:41]
	s_cbranch_vccnz .LBB0_1291
	ds_read_b128 v[174:177], v231 offset:16384
	ds_read_b128 v[190:193], v231 offset:17408
	ds_read_b128 v[170:173], v231 offset:18432
	ds_read_b128 v[186:189], v231 offset:19456
	ds_read_b128 v[166:169], v231 offset:20480
	ds_read_b128 v[182:185], v231 offset:21504
	ds_read_b128 v[162:165], v231 offset:22528
	ds_read_b128 v[178:181], v231 offset:23552
.LBB0_1291:
	s_add_u32 s52, s36, s48
	s_addc_u32 s53, s37, s49
	s_add_u32 s56, s52, 0x440000
	s_addc_u32 s57, s53, 0
	s_cmp_eq_u32 s48, 0x3fc0000
	s_cselect_b64 s[58:59], -1, 0
	s_and_b64 s[52:53], s[58:59], exec
	s_cselect_b32 s53, s31, s63
	s_cselect_b32 s52, s61, s62
	s_mov_b32 m0, s9
	s_cselect_b32 s57, s19, s57
	s_cselect_b32 s56, s29, s56
	s_add_u32 s68, s52, 0x4000
	global_load_lds_dwordx4 v194, s[52:53]
	s_mov_b32 m0, s10
	s_addc_u32 s69, s53, 0
	global_load_lds_dwordx4 v196, s[52:53]
	s_mov_b32 m0, s11
	s_and_b64 vcc, exec, s[42:43]
	global_load_lds_dwordx4 v194, s[68:69]
	s_mov_b32 m0, s12
	s_nop 0
	global_load_lds_dwordx4 v196, s[68:69]
	s_mov_b64 s[98:99], s[56:57]
	s_waitcnt vmcnt(6)
	s_waitcnt lgkmcnt(0)
	s_barrier
	s_cbranch_vccnz .LBB0_1293
	s_waitcnt lgkmcnt(0)
	v_mfma_f32_16x16x32_bf16 v[62:65], v[146:149], v[174:177], v[62:65]
	v_mfma_f32_16x16x32_bf16 v[58:61], v[154:157], v[174:177], v[58:61]
	v_mfma_f32_16x16x32_bf16 v[46:49], v[146:149], v[170:173], v[46:49]
	v_mfma_f32_16x16x32_bf16 v[42:45], v[154:157], v[170:173], v[42:45]
	v_mfma_f32_16x16x32_bf16 v[30:33], v[146:149], v[166:169], v[30:33]
	v_mfma_f32_16x16x32_bf16 v[26:29], v[154:157], v[166:169], v[26:29]
	v_mfma_f32_16x16x32_bf16 v[14:17], v[146:149], v[162:165], v[14:17]
	v_mfma_f32_16x16x32_bf16 v[10:13], v[154:157], v[162:165], v[10:13]
	v_mfma_f32_16x16x32_bf16 v[62:65], v[150:153], v[190:193], v[62:65]
	v_mfma_f32_16x16x32_bf16 v[58:61], v[158:161], v[190:193], v[58:61]
	v_mfma_f32_16x16x32_bf16 v[46:49], v[150:153], v[186:189], v[46:49]
	v_mfma_f32_16x16x32_bf16 v[42:45], v[158:161], v[186:189], v[42:45]
	v_mfma_f32_16x16x32_bf16 v[30:33], v[150:153], v[182:185], v[30:33]
	v_mfma_f32_16x16x32_bf16 v[26:29], v[158:161], v[182:185], v[26:29]
	v_mfma_f32_16x16x32_bf16 v[14:17], v[150:153], v[178:181], v[14:17]
	v_mfma_f32_16x16x32_bf16 v[10:13], v[158:161], v[178:181], v[10:13]
	v_mfma_f32_16x16x32_bf16 v[54:57], v[130:133], v[174:177], v[54:57]
	v_mfma_f32_16x16x32_bf16 v[50:53], v[138:141], v[174:177], v[50:53]
	v_mfma_f32_16x16x32_bf16 v[38:41], v[130:133], v[170:173], v[38:41]
	v_mfma_f32_16x16x32_bf16 v[34:37], v[138:141], v[170:173], v[34:37]
	v_mfma_f32_16x16x32_bf16 v[22:25], v[130:133], v[166:169], v[22:25]
	v_mfma_f32_16x16x32_bf16 v[18:21], v[138:141], v[166:169], v[18:21]
	v_mfma_f32_16x16x32_bf16 v[6:9], v[130:133], v[162:165], v[6:9]
	v_mfma_f32_16x16x32_bf16 v[2:5], v[138:141], v[162:165], v[2:5]
	v_mfma_f32_16x16x32_bf16 v[54:57], v[134:137], v[190:193], v[54:57]
	v_mfma_f32_16x16x32_bf16 v[50:53], v[142:145], v[190:193], v[50:53]
	v_mfma_f32_16x16x32_bf16 v[38:41], v[134:137], v[186:189], v[38:41]
	v_mfma_f32_16x16x32_bf16 v[34:37], v[142:145], v[186:189], v[34:37]
	v_mfma_f32_16x16x32_bf16 v[22:25], v[134:137], v[182:185], v[22:25]
	v_mfma_f32_16x16x32_bf16 v[18:21], v[142:145], v[182:185], v[18:21]
	v_mfma_f32_16x16x32_bf16 v[6:9], v[134:137], v[178:181], v[6:9]
	v_mfma_f32_16x16x32_bf16 v[2:5], v[142:145], v[178:181], v[2:5]
.LBB0_1293:
	s_and_b64 vcc, s[34:35], s[58:59]
	v_cndmask_b32_e64 v131, v221, 0, vcc
	v_cndmask_b32_e32 v130, v220, v198, vcc
	v_lshl_add_u64 v[234:235], s[56:57], 0, v[130:131]
	s_barrier
	s_mov_b32 m0, s8
	s_nop 0
	global_load_lds_dwordx4 v194, s[98:99]
	s_mov_b32 m0, s13
	s_nop 0
	global_load_lds_dwordx4 v196, s[98:99]
	v_add_u32_e32 v130, 0x18000, v229
	v_add_u32_e32 v142, 0x1c000, v229
	ds_read_b128 v[146:149], v130
	ds_read_b128 v[150:153], v130 offset:1024
	ds_read_b128 v[154:157], v130 offset:2048
	ds_read_b128 v[158:161], v130 offset:3072
	ds_read_b128 v[130:133], v142
	ds_read_b128 v[134:137], v142 offset:1024
	ds_read_b128 v[138:141], v142 offset:2048
	ds_read_b128 v[142:145], v142 offset:3072
	s_mov_b32 m0, s14
	v_lshl_add_u64 v[236:237], v[234:235], 0, v[194:195]
	s_waitcnt lgkmcnt(0)
	ds_read_b128 v[174:177], v231 offset:32768
	ds_read_b128 v[190:193], v231 offset:33792
	ds_read_b128 v[170:173], v231 offset:34816
	ds_read_b128 v[186:189], v231 offset:35840
	ds_read_b128 v[166:169], v231 offset:36864
	ds_read_b128 v[182:185], v231 offset:37888
	ds_read_b128 v[162:165], v231 offset:38912
	ds_read_b128 v[178:181], v231 offset:39936
	global_load_lds_dwordx4 v[236:237], off
	v_lshl_add_u64 v[234:235], v[234:235], 0, v[196:197]
	s_mov_b32 m0, s15
	s_nop 0
	global_load_lds_dwordx4 v[234:235], off
	s_waitcnt vmcnt(8)
	s_waitcnt lgkmcnt(0)
	s_barrier
	s_waitcnt lgkmcnt(0)
	v_mfma_f32_16x16x32_bf16 v[126:129], v[146:149], v[174:177], v[126:129]
	v_mfma_f32_16x16x32_bf16 v[122:125], v[154:157], v[174:177], v[122:125]
	v_mfma_f32_16x16x32_bf16 v[118:121], v[146:149], v[170:173], v[118:121]
	v_mfma_f32_16x16x32_bf16 v[110:113], v[154:157], v[170:173], v[110:113]
	v_mfma_f32_16x16x32_bf16 v[102:105], v[146:149], v[166:169], v[102:105]
	v_mfma_f32_16x16x32_bf16 v[94:97], v[154:157], v[166:169], v[94:97]
	v_mfma_f32_16x16x32_bf16 v[86:89], v[146:149], v[162:165], v[86:89]
	v_mfma_f32_16x16x32_bf16 v[78:81], v[154:157], v[162:165], v[78:81]
	v_mfma_f32_16x16x32_bf16 v[126:129], v[150:153], v[190:193], v[126:129]
	v_mfma_f32_16x16x32_bf16 v[122:125], v[158:161], v[190:193], v[122:125]
	v_mfma_f32_16x16x32_bf16 v[118:121], v[150:153], v[186:189], v[118:121]
	v_mfma_f32_16x16x32_bf16 v[110:113], v[158:161], v[186:189], v[110:113]
	v_mfma_f32_16x16x32_bf16 v[102:105], v[150:153], v[182:185], v[102:105]
	v_mfma_f32_16x16x32_bf16 v[94:97], v[158:161], v[182:185], v[94:97]
	v_mfma_f32_16x16x32_bf16 v[86:89], v[150:153], v[178:181], v[86:89]
	v_mfma_f32_16x16x32_bf16 v[78:81], v[158:161], v[178:181], v[78:81]
	v_mfma_f32_16x16x32_bf16 v[114:117], v[130:133], v[174:177], v[114:117]
	v_mfma_f32_16x16x32_bf16 v[106:109], v[138:141], v[174:177], v[106:109]
	v_mfma_f32_16x16x32_bf16 v[98:101], v[130:133], v[170:173], v[98:101]
	v_mfma_f32_16x16x32_bf16 v[90:93], v[138:141], v[170:173], v[90:93]
	v_mfma_f32_16x16x32_bf16 v[82:85], v[130:133], v[166:169], v[82:85]
	v_mfma_f32_16x16x32_bf16 v[74:77], v[138:141], v[166:169], v[74:77]
	v_mfma_f32_16x16x32_bf16 v[70:73], v[130:133], v[162:165], v[70:73]
	v_mfma_f32_16x16x32_bf16 v[66:69], v[138:141], v[162:165], v[66:69]
	v_mfma_f32_16x16x32_bf16 v[114:117], v[134:137], v[190:193], v[114:117]
	v_mfma_f32_16x16x32_bf16 v[106:109], v[142:145], v[190:193], v[106:109]
	v_mfma_f32_16x16x32_bf16 v[98:101], v[134:137], v[186:189], v[98:101]
	v_mfma_f32_16x16x32_bf16 v[90:93], v[142:145], v[186:189], v[90:93]
	v_mfma_f32_16x16x32_bf16 v[82:85], v[134:137], v[182:185], v[82:85]
	v_mfma_f32_16x16x32_bf16 v[74:77], v[142:145], v[182:185], v[74:77]
	v_mfma_f32_16x16x32_bf16 v[70:73], v[134:137], v[178:181], v[70:73]
	v_mfma_f32_16x16x32_bf16 v[66:69], v[142:145], v[178:181], v[66:69]
	s_barrier
	s_and_b64 vcc, exec, s[42:43]
	s_cbranch_vccnz .LBB0_1295
	ds_read_b128 v[174:177], v231 offset:49152
	ds_read_b128 v[190:193], v231 offset:50176
	ds_read_b128 v[170:173], v231 offset:51200
	ds_read_b128 v[186:189], v231 offset:52224
	ds_read_b128 v[166:169], v231 offset:53248
	ds_read_b128 v[182:185], v231 offset:54272
	ds_read_b128 v[162:165], v231 offset:55296
	ds_read_b128 v[178:181], v231 offset:56320
.LBB0_1295:
	s_add_u32 s58, s52, 0x40000
	s_addc_u32 s59, s53, 0
	s_add_u32 s56, s56, 0x220000
	s_addc_u32 s57, s57, 0
	s_mov_b32 m0, s16
	s_add_u32 s52, s52, 0x44000
	global_load_lds_dwordx4 v194, s[58:59]
	s_mov_b32 m0, s17
	s_addc_u32 s53, s53, 0
	global_load_lds_dwordx4 v196, s[58:59]
	s_mov_b32 m0, s55
	s_and_b64 vcc, exec, s[42:43]
	global_load_lds_dwordx4 v194, s[52:53]
	s_mov_b32 m0, s60
	s_nop 0
	global_load_lds_dwordx4 v196, s[52:53]
	s_mov_b64 s[100:101], s[56:57]
	s_waitcnt vmcnt(6)
	s_waitcnt lgkmcnt(0)
	s_barrier
	s_cbranch_vccnz .LBB0_1288
	s_waitcnt lgkmcnt(0)
	v_mfma_f32_16x16x32_bf16 v[62:65], v[146:149], v[174:177], v[62:65]
	v_mfma_f32_16x16x32_bf16 v[58:61], v[154:157], v[174:177], v[58:61]
	v_mfma_f32_16x16x32_bf16 v[46:49], v[146:149], v[170:173], v[46:49]
	v_mfma_f32_16x16x32_bf16 v[42:45], v[154:157], v[170:173], v[42:45]
	v_mfma_f32_16x16x32_bf16 v[30:33], v[146:149], v[166:169], v[30:33]
	v_mfma_f32_16x16x32_bf16 v[26:29], v[154:157], v[166:169], v[26:29]
	v_mfma_f32_16x16x32_bf16 v[14:17], v[146:149], v[162:165], v[14:17]
	v_mfma_f32_16x16x32_bf16 v[10:13], v[154:157], v[162:165], v[10:13]
	v_mfma_f32_16x16x32_bf16 v[62:65], v[150:153], v[190:193], v[62:65]
	v_mfma_f32_16x16x32_bf16 v[58:61], v[158:161], v[190:193], v[58:61]
	v_mfma_f32_16x16x32_bf16 v[46:49], v[150:153], v[186:189], v[46:49]
	v_mfma_f32_16x16x32_bf16 v[42:45], v[158:161], v[186:189], v[42:45]
	v_mfma_f32_16x16x32_bf16 v[30:33], v[150:153], v[182:185], v[30:33]
	v_mfma_f32_16x16x32_bf16 v[26:29], v[158:161], v[182:185], v[26:29]
	v_mfma_f32_16x16x32_bf16 v[14:17], v[150:153], v[178:181], v[14:17]
	v_mfma_f32_16x16x32_bf16 v[10:13], v[158:161], v[178:181], v[10:13]
	v_mfma_f32_16x16x32_bf16 v[54:57], v[130:133], v[174:177], v[54:57]
	v_mfma_f32_16x16x32_bf16 v[50:53], v[138:141], v[174:177], v[50:53]
	v_mfma_f32_16x16x32_bf16 v[38:41], v[130:133], v[170:173], v[38:41]
	v_mfma_f32_16x16x32_bf16 v[34:37], v[138:141], v[170:173], v[34:37]
	v_mfma_f32_16x16x32_bf16 v[22:25], v[130:133], v[166:169], v[22:25]
	v_mfma_f32_16x16x32_bf16 v[18:21], v[138:141], v[166:169], v[18:21]
	v_mfma_f32_16x16x32_bf16 v[6:9], v[130:133], v[162:165], v[6:9]
	v_mfma_f32_16x16x32_bf16 v[2:5], v[138:141], v[162:165], v[2:5]
	v_mfma_f32_16x16x32_bf16 v[54:57], v[134:137], v[190:193], v[54:57]
	v_mfma_f32_16x16x32_bf16 v[50:53], v[142:145], v[190:193], v[50:53]
	v_mfma_f32_16x16x32_bf16 v[38:41], v[134:137], v[186:189], v[38:41]
	v_mfma_f32_16x16x32_bf16 v[34:37], v[142:145], v[186:189], v[34:37]
	v_mfma_f32_16x16x32_bf16 v[22:25], v[134:137], v[182:185], v[22:25]
	v_mfma_f32_16x16x32_bf16 v[18:21], v[142:145], v[182:185], v[18:21]
	v_mfma_f32_16x16x32_bf16 v[6:9], v[134:137], v[178:181], v[6:9]
	v_mfma_f32_16x16x32_bf16 v[2:5], v[142:145], v[178:181], v[2:5]
	s_branch .LBB0_1288

.LBB0_1612:
	s_mov_b32 m0, s54
	s_nop 0
	global_load_lds_dwordx4 v194, s[100:101]
	s_mov_b32 m0, s55
	s_nop 0
	global_load_lds_dwordx4 v196, s[100:101]
	v_add_u32_e32 v1, 0x10000, v232
	ds_read_b128 v[146:149], v1
	ds_read_b128 v[150:153], v1 offset:1024
	ds_read_b128 v[154:157], v1 offset:2048
	ds_read_b128 v[158:161], v1 offset:3072
	v_add_u32_e32 v1, 0x14000, v232
	ds_read_b128 v[130:133], v1
	ds_read_b128 v[134:137], v1 offset:1024
	ds_read_b128 v[138:141], v1 offset:2048
	ds_read_b128 v[142:145], v1 offset:3072
	v_lshl_add_u64 v[236:237], v[226:227], 0, s[48:49]
	s_add_i32 m0, s9, 0xc000
	s_waitcnt lgkmcnt(0)
	ds_read_b128 v[174:177], v233
	ds_read_b128 v[190:193], v233 offset:1024
	ds_read_b128 v[170:173], v233 offset:2048
	ds_read_b128 v[186:189], v233 offset:3072
	ds_read_b128 v[166:169], v233 offset:4096
	ds_read_b128 v[182:185], v233 offset:5120
	ds_read_b128 v[162:165], v233 offset:6144
	ds_read_b128 v[178:181], v233 offset:7168
	global_load_lds_dwordx4 v[236:237], off
	v_lshl_add_u64 v[236:237], v[228:229], 0, s[48:49]
	s_add_i32 m0, s9, 0xe000
	s_nop 0
	global_load_lds_dwordx4 v[236:237], off
	s_waitcnt vmcnt(8)
	s_waitcnt lgkmcnt(0)
	s_barrier
	s_waitcnt lgkmcnt(0)
	v_mfma_f32_16x16x32_bf16 v[126:129], v[146:149], v[174:177], v[126:129]
	v_mfma_f32_16x16x32_bf16 v[122:125], v[154:157], v[174:177], v[122:125]
	v_mfma_f32_16x16x32_bf16 v[118:121], v[146:149], v[170:173], v[118:121]
	v_mfma_f32_16x16x32_bf16 v[110:113], v[154:157], v[170:173], v[110:113]
	v_mfma_f32_16x16x32_bf16 v[102:105], v[146:149], v[166:169], v[102:105]
	v_mfma_f32_16x16x32_bf16 v[94:97], v[154:157], v[166:169], v[94:97]
	v_mfma_f32_16x16x32_bf16 v[86:89], v[146:149], v[162:165], v[86:89]
	v_mfma_f32_16x16x32_bf16 v[78:81], v[154:157], v[162:165], v[78:81]
	v_mfma_f32_16x16x32_bf16 v[126:129], v[150:153], v[190:193], v[126:129]
	v_mfma_f32_16x16x32_bf16 v[122:125], v[158:161], v[190:193], v[122:125]
	v_mfma_f32_16x16x32_bf16 v[118:121], v[150:153], v[186:189], v[118:121]
	v_mfma_f32_16x16x32_bf16 v[110:113], v[158:161], v[186:189], v[110:113]
	v_mfma_f32_16x16x32_bf16 v[102:105], v[150:153], v[182:185], v[102:105]
	v_mfma_f32_16x16x32_bf16 v[94:97], v[158:161], v[182:185], v[94:97]
	v_mfma_f32_16x16x32_bf16 v[86:89], v[150:153], v[178:181], v[86:89]
	v_mfma_f32_16x16x32_bf16 v[78:81], v[158:161], v[178:181], v[78:81]
	v_mfma_f32_16x16x32_bf16 v[114:117], v[130:133], v[174:177], v[114:117]
	v_mfma_f32_16x16x32_bf16 v[106:109], v[138:141], v[174:177], v[106:109]
	v_mfma_f32_16x16x32_bf16 v[98:101], v[130:133], v[170:173], v[98:101]
	v_mfma_f32_16x16x32_bf16 v[90:93], v[138:141], v[170:173], v[90:93]
	v_mfma_f32_16x16x32_bf16 v[82:85], v[130:133], v[166:169], v[82:85]
	v_mfma_f32_16x16x32_bf16 v[74:77], v[138:141], v[166:169], v[74:77]
	v_mfma_f32_16x16x32_bf16 v[70:73], v[130:133], v[162:165], v[70:73]
	v_mfma_f32_16x16x32_bf16 v[66:69], v[138:141], v[162:165], v[66:69]
	v_mfma_f32_16x16x32_bf16 v[114:117], v[134:137], v[190:193], v[114:117]
	v_mfma_f32_16x16x32_bf16 v[106:109], v[142:145], v[190:193], v[106:109]
	v_mfma_f32_16x16x32_bf16 v[98:101], v[134:137], v[186:189], v[98:101]
	v_mfma_f32_16x16x32_bf16 v[90:93], v[142:145], v[186:189], v[90:93]
	v_mfma_f32_16x16x32_bf16 v[82:85], v[134:137], v[182:185], v[82:85]
	v_mfma_f32_16x16x32_bf16 v[74:77], v[142:145], v[182:185], v[74:77]
	v_mfma_f32_16x16x32_bf16 v[70:73], v[134:137], v[178:181], v[70:73]
	v_mfma_f32_16x16x32_bf16 v[66:69], v[142:145], v[178:181], v[66:69]
	s_barrier
	v_cndmask_b32_e64 v1, 0, 1, s[40:41]
	v_cmp_ne_u32_e64 s[42:43], 1, v1
	s_andn2_b64 vcc, exec, s[40:41]
	s_cbranch_vccnz .LBB0_1614
	ds_read_b128 v[174:177], v233 offset:16384
	ds_read_b128 v[190:193], v233 offset:17408
	ds_read_b128 v[170:173], v233 offset:18432
	ds_read_b128 v[186:189], v233 offset:19456
	ds_read_b128 v[166:169], v233 offset:20480
	ds_read_b128 v[182:185], v233 offset:21504
	ds_read_b128 v[162:165], v233 offset:22528
	ds_read_b128 v[178:181], v233 offset:23552
.LBB0_1614:
	s_add_u32 s50, s46, s48
	s_addc_u32 s51, s47, s49
	s_add_u32 s52, s50, 0x440000
	s_addc_u32 s53, s51, 0
	s_cmp_eq_u32 s48, 0x3fc0000
	s_cselect_b64 s[56:57], -1, 0
	s_and_b64 s[50:51], s[56:57], exec
	s_cselect_b32 s51, s31, s61
	s_cselect_b32 s50, s35, s60
	s_mov_b32 m0, s10
	s_cselect_b32 s53, s19, s53
	s_cselect_b32 s52, s20, s52
	s_add_u32 s68, s50, 0x4000
	global_load_lds_dwordx4 v194, s[50:51]
	s_mov_b32 m0, s11
	s_addc_u32 s69, s51, 0
	global_load_lds_dwordx4 v196, s[50:51]
	s_mov_b32 m0, s12
	s_and_b64 vcc, exec, s[42:43]
	global_load_lds_dwordx4 v194, s[68:69]
	s_mov_b32 m0, s13
	s_nop 0
	global_load_lds_dwordx4 v196, s[68:69]
	s_mov_b64 s[98:99], s[52:53]
	s_waitcnt vmcnt(6)
	s_waitcnt lgkmcnt(0)
	s_barrier
	s_cbranch_vccnz .LBB0_1616
	s_waitcnt lgkmcnt(0)
	v_mfma_f32_16x16x32_bf16 v[62:65], v[146:149], v[174:177], v[62:65]
	v_mfma_f32_16x16x32_bf16 v[58:61], v[154:157], v[174:177], v[58:61]
	v_mfma_f32_16x16x32_bf16 v[46:49], v[146:149], v[170:173], v[46:49]
	v_mfma_f32_16x16x32_bf16 v[42:45], v[154:157], v[170:173], v[42:45]
	v_mfma_f32_16x16x32_bf16 v[30:33], v[146:149], v[166:169], v[30:33]
	v_mfma_f32_16x16x32_bf16 v[26:29], v[154:157], v[166:169], v[26:29]
	v_mfma_f32_16x16x32_bf16 v[14:17], v[146:149], v[162:165], v[14:17]
	v_mfma_f32_16x16x32_bf16 v[10:13], v[154:157], v[162:165], v[10:13]
	v_mfma_f32_16x16x32_bf16 v[62:65], v[150:153], v[190:193], v[62:65]
	v_mfma_f32_16x16x32_bf16 v[58:61], v[158:161], v[190:193], v[58:61]
	v_mfma_f32_16x16x32_bf16 v[46:49], v[150:153], v[186:189], v[46:49]
	v_mfma_f32_16x16x32_bf16 v[42:45], v[158:161], v[186:189], v[42:45]
	v_mfma_f32_16x16x32_bf16 v[30:33], v[150:153], v[182:185], v[30:33]
	v_mfma_f32_16x16x32_bf16 v[26:29], v[158:161], v[182:185], v[26:29]
	v_mfma_f32_16x16x32_bf16 v[14:17], v[150:153], v[178:181], v[14:17]
	v_mfma_f32_16x16x32_bf16 v[10:13], v[158:161], v[178:181], v[10:13]
	v_mfma_f32_16x16x32_bf16 v[54:57], v[130:133], v[174:177], v[54:57]
	v_mfma_f32_16x16x32_bf16 v[50:53], v[138:141], v[174:177], v[50:53]
	v_mfma_f32_16x16x32_bf16 v[38:41], v[130:133], v[170:173], v[38:41]
	v_mfma_f32_16x16x32_bf16 v[34:37], v[138:141], v[170:173], v[34:37]
	v_mfma_f32_16x16x32_bf16 v[22:25], v[130:133], v[166:169], v[22:25]
	v_mfma_f32_16x16x32_bf16 v[18:21], v[138:141], v[166:169], v[18:21]
	v_mfma_f32_16x16x32_bf16 v[6:9], v[130:133], v[162:165], v[6:9]
	v_mfma_f32_16x16x32_bf16 v[2:5], v[138:141], v[162:165], v[2:5]
	v_mfma_f32_16x16x32_bf16 v[54:57], v[134:137], v[190:193], v[54:57]
	v_mfma_f32_16x16x32_bf16 v[50:53], v[142:145], v[190:193], v[50:53]
	v_mfma_f32_16x16x32_bf16 v[38:41], v[134:137], v[186:189], v[38:41]
	v_mfma_f32_16x16x32_bf16 v[34:37], v[142:145], v[186:189], v[34:37]
	v_mfma_f32_16x16x32_bf16 v[22:25], v[134:137], v[182:185], v[22:25]
	v_mfma_f32_16x16x32_bf16 v[18:21], v[142:145], v[182:185], v[18:21]
	v_mfma_f32_16x16x32_bf16 v[6:9], v[134:137], v[178:181], v[6:9]
	v_mfma_f32_16x16x32_bf16 v[2:5], v[142:145], v[178:181], v[2:5]
.LBB0_1616:
	s_and_b64 vcc, s[38:39], s[56:57]
	v_cndmask_b32_e64 v131, v225, 0, vcc
	v_cndmask_b32_e32 v130, v224, v198, vcc
	v_lshl_add_u64 v[236:237], s[52:53], 0, v[130:131]
	s_barrier
	s_mov_b32 m0, s9
	s_nop 0
	global_load_lds_dwordx4 v194, s[98:99]
	s_mov_b32 m0, s14
	s_nop 0
	global_load_lds_dwordx4 v196, s[98:99]
	v_add_u32_e32 v1, 0x18000, v232
	ds_read_b128 v[146:149], v1
	ds_read_b128 v[150:153], v1 offset:1024
	ds_read_b128 v[154:157], v1 offset:2048
	ds_read_b128 v[158:161], v1 offset:3072
	v_add_u32_e32 v1, 0x1c000, v232
	ds_read_b128 v[130:133], v1
	ds_read_b128 v[134:137], v1 offset:1024
	ds_read_b128 v[138:141], v1 offset:2048
	ds_read_b128 v[142:145], v1 offset:3072
	s_mov_b32 m0, s15
	v_lshl_add_u64 v[238:239], v[236:237], 0, v[194:195]
	s_waitcnt lgkmcnt(0)
	ds_read_b128 v[174:177], v233 offset:32768
	ds_read_b128 v[190:193], v233 offset:33792
	ds_read_b128 v[170:173], v233 offset:34816
	ds_read_b128 v[186:189], v233 offset:35840
	ds_read_b128 v[166:169], v233 offset:36864
	ds_read_b128 v[182:185], v233 offset:37888
	ds_read_b128 v[162:165], v233 offset:38912
	ds_read_b128 v[178:181], v233 offset:39936
	global_load_lds_dwordx4 v[238:239], off
	v_lshl_add_u64 v[236:237], v[236:237], 0, v[196:197]
	s_mov_b32 m0, s16
	s_nop 0
	global_load_lds_dwordx4 v[236:237], off
	s_waitcnt vmcnt(8)
	s_waitcnt lgkmcnt(0)
	s_barrier
	s_waitcnt lgkmcnt(0)
	v_mfma_f32_16x16x32_bf16 v[126:129], v[146:149], v[174:177], v[126:129]
	v_mfma_f32_16x16x32_bf16 v[122:125], v[154:157], v[174:177], v[122:125]
	v_mfma_f32_16x16x32_bf16 v[118:121], v[146:149], v[170:173], v[118:121]
	v_mfma_f32_16x16x32_bf16 v[110:113], v[154:157], v[170:173], v[110:113]
	v_mfma_f32_16x16x32_bf16 v[102:105], v[146:149], v[166:169], v[102:105]
	v_mfma_f32_16x16x32_bf16 v[94:97], v[154:157], v[166:169], v[94:97]
	v_mfma_f32_16x16x32_bf16 v[86:89], v[146:149], v[162:165], v[86:89]
	v_mfma_f32_16x16x32_bf16 v[78:81], v[154:157], v[162:165], v[78:81]
	v_mfma_f32_16x16x32_bf16 v[126:129], v[150:153], v[190:193], v[126:129]
	v_mfma_f32_16x16x32_bf16 v[122:125], v[158:161], v[190:193], v[122:125]
	v_mfma_f32_16x16x32_bf16 v[118:121], v[150:153], v[186:189], v[118:121]
	v_mfma_f32_16x16x32_bf16 v[110:113], v[158:161], v[186:189], v[110:113]
	v_mfma_f32_16x16x32_bf16 v[102:105], v[150:153], v[182:185], v[102:105]
	v_mfma_f32_16x16x32_bf16 v[94:97], v[158:161], v[182:185], v[94:97]
	v_mfma_f32_16x16x32_bf16 v[86:89], v[150:153], v[178:181], v[86:89]
	v_mfma_f32_16x16x32_bf16 v[78:81], v[158:161], v[178:181], v[78:81]
	v_mfma_f32_16x16x32_bf16 v[114:117], v[130:133], v[174:177], v[114:117]
	v_mfma_f32_16x16x32_bf16 v[106:109], v[138:141], v[174:177], v[106:109]
	v_mfma_f32_16x16x32_bf16 v[98:101], v[130:133], v[170:173], v[98:101]
	v_mfma_f32_16x16x32_bf16 v[90:93], v[138:141], v[170:173], v[90:93]
	v_mfma_f32_16x16x32_bf16 v[82:85], v[130:133], v[166:169], v[82:85]
	v_mfma_f32_16x16x32_bf16 v[74:77], v[138:141], v[166:169], v[74:77]
	v_mfma_f32_16x16x32_bf16 v[70:73], v[130:133], v[162:165], v[70:73]
	v_mfma_f32_16x16x32_bf16 v[66:69], v[138:141], v[162:165], v[66:69]
	v_mfma_f32_16x16x32_bf16 v[114:117], v[134:137], v[190:193], v[114:117]
	v_mfma_f32_16x16x32_bf16 v[106:109], v[142:145], v[190:193], v[106:109]
	v_mfma_f32_16x16x32_bf16 v[98:101], v[134:137], v[186:189], v[98:101]
	v_mfma_f32_16x16x32_bf16 v[90:93], v[142:145], v[186:189], v[90:93]
	v_mfma_f32_16x16x32_bf16 v[82:85], v[134:137], v[182:185], v[82:85]
	v_mfma_f32_16x16x32_bf16 v[74:77], v[142:145], v[182:185], v[74:77]
	v_mfma_f32_16x16x32_bf16 v[70:73], v[134:137], v[178:181], v[70:73]
	v_mfma_f32_16x16x32_bf16 v[66:69], v[142:145], v[178:181], v[66:69]
	s_barrier
	s_and_b64 vcc, exec, s[42:43]
	s_cbranch_vccnz .LBB0_1618
	ds_read_b128 v[174:177], v233 offset:49152
	ds_read_b128 v[190:193], v233 offset:50176
	ds_read_b128 v[170:173], v233 offset:51200
	ds_read_b128 v[186:189], v233 offset:52224
	ds_read_b128 v[166:169], v233 offset:53248
	ds_read_b128 v[182:185], v233 offset:54272
	ds_read_b128 v[162:165], v233 offset:55296
	ds_read_b128 v[178:181], v233 offset:56320
.LBB0_1618:
	s_add_u32 s56, s50, 0x40000
	s_addc_u32 s57, s51, 0
	s_add_u32 s52, s52, 0x220000
	s_addc_u32 s53, s53, 0
	s_mov_b32 m0, s17
	s_add_u32 s50, s50, 0x44000
	global_load_lds_dwordx4 v194, s[56:57]
	s_mov_b32 m0, s29
	s_addc_u32 s51, s51, 0
	global_load_lds_dwordx4 v196, s[56:57]
	s_mov_b32 m0, s58
	s_and_b64 vcc, exec, s[42:43]
	global_load_lds_dwordx4 v194, s[50:51]
	s_mov_b32 m0, s59
	s_nop 0
	global_load_lds_dwordx4 v196, s[50:51]
	s_mov_b64 s[100:101], s[52:53]
	s_waitcnt vmcnt(6)
	s_waitcnt lgkmcnt(0)
	s_barrier
	s_cbranch_vccnz .LBB0_1611
	s_waitcnt lgkmcnt(0)
	v_mfma_f32_16x16x32_bf16 v[62:65], v[146:149], v[174:177], v[62:65]
	v_mfma_f32_16x16x32_bf16 v[58:61], v[154:157], v[174:177], v[58:61]
	v_mfma_f32_16x16x32_bf16 v[46:49], v[146:149], v[170:173], v[46:49]
	v_mfma_f32_16x16x32_bf16 v[42:45], v[154:157], v[170:173], v[42:45]
	v_mfma_f32_16x16x32_bf16 v[30:33], v[146:149], v[166:169], v[30:33]
	v_mfma_f32_16x16x32_bf16 v[26:29], v[154:157], v[166:169], v[26:29]
	v_mfma_f32_16x16x32_bf16 v[14:17], v[146:149], v[162:165], v[14:17]
	v_mfma_f32_16x16x32_bf16 v[10:13], v[154:157], v[162:165], v[10:13]
	v_mfma_f32_16x16x32_bf16 v[62:65], v[150:153], v[190:193], v[62:65]
	v_mfma_f32_16x16x32_bf16 v[58:61], v[158:161], v[190:193], v[58:61]
	v_mfma_f32_16x16x32_bf16 v[46:49], v[150:153], v[186:189], v[46:49]
	v_mfma_f32_16x16x32_bf16 v[42:45], v[158:161], v[186:189], v[42:45]
	v_mfma_f32_16x16x32_bf16 v[30:33], v[150:153], v[182:185], v[30:33]
	v_mfma_f32_16x16x32_bf16 v[26:29], v[158:161], v[182:185], v[26:29]
	v_mfma_f32_16x16x32_bf16 v[14:17], v[150:153], v[178:181], v[14:17]
	v_mfma_f32_16x16x32_bf16 v[10:13], v[158:161], v[178:181], v[10:13]
	v_mfma_f32_16x16x32_bf16 v[54:57], v[130:133], v[174:177], v[54:57]
	v_mfma_f32_16x16x32_bf16 v[50:53], v[138:141], v[174:177], v[50:53]
	v_mfma_f32_16x16x32_bf16 v[38:41], v[130:133], v[170:173], v[38:41]
	v_mfma_f32_16x16x32_bf16 v[34:37], v[138:141], v[170:173], v[34:37]
	v_mfma_f32_16x16x32_bf16 v[22:25], v[130:133], v[166:169], v[22:25]
	v_mfma_f32_16x16x32_bf16 v[18:21], v[138:141], v[166:169], v[18:21]
	v_mfma_f32_16x16x32_bf16 v[6:9], v[130:133], v[162:165], v[6:9]
	v_mfma_f32_16x16x32_bf16 v[2:5], v[138:141], v[162:165], v[2:5]
	v_mfma_f32_16x16x32_bf16 v[54:57], v[134:137], v[190:193], v[54:57]
	v_mfma_f32_16x16x32_bf16 v[50:53], v[142:145], v[190:193], v[50:53]
	v_mfma_f32_16x16x32_bf16 v[38:41], v[134:137], v[186:189], v[38:41]
	v_mfma_f32_16x16x32_bf16 v[34:37], v[142:145], v[186:189], v[34:37]
	v_mfma_f32_16x16x32_bf16 v[22:25], v[134:137], v[182:185], v[22:25]
	v_mfma_f32_16x16x32_bf16 v[18:21], v[142:145], v[182:185], v[18:21]
	v_mfma_f32_16x16x32_bf16 v[6:9], v[134:137], v[178:181], v[6:9]
	v_mfma_f32_16x16x32_bf16 v[2:5], v[142:145], v[178:181], v[2:5]
	s_branch .LBB0_1611
